# scan consumer: loads at step head, wait per 2 steps, plus group-3 transposes deferred into the next chunk's DPP gaps
# speedup vs baseline: 1.0165x; 1.0021x over previous
.Lscan_cons_chunk:
	v_cndmask_b32_e64 v2, v4, v5, s[42:43]
	v_add_lshl_u32 v2, v2, s80, 10
	v_mov_b32_e32 v3, v180
	s_add_i32 s28, s28, 0x10000
	v_lshl_add_u64 v[2:3], v[0:1], 0, v[2:3]
	v_add_u32_e32 v5, 64, v5
	v_subrev_u32_e32 v4, 64, v4
	s_waitcnt lgkmcnt(0)
	ds_read_b128 v[88:91], v10 offset:2304
	ds_read_b128 v[96:99], v10 offset:2816
	ds_read_b128 v[92:95], v10 offset:2560
	v_fma_mix_f32 v12, v6, v20, v180 op_sel_hi:[0,1,0]
	v_fma_mix_f32 v12, v7, v20, v12 op_sel:[0,1,0] op_sel_hi:[0,1,0]
	v_fma_mix_f32 v12, v8, v21, v12 op_sel_hi:[0,1,0]
	v_fma_mix_f32 v12, v9, v21, v12 op_sel:[0,1,0] op_sel_hi:[0,1,0]
	s_nop 1
	v_add_f32_dpp v12, v12, v12 row_ror:1 row_mask:0xf bank_mask:0xf bound_ctrl:1
	s_nop 1
	v_add_f32_dpp v12, v12, v12 row_ror:2 row_mask:0xf bank_mask:0xf bound_ctrl:1
	v_pk_fma_f32 v[48:49], v[28:29], v[66:67], v[6:7] op_sel_hi:[1,0,1]
	v_pk_fma_f32 v[50:51], v[30:31], v[66:67], v[8:9] op_sel_hi:[1,0,1]
	v_add_f32_dpp v12, v12, v12 row_ror:4 row_mask:0xf bank_mask:0xf bound_ctrl:1
	v_add_f32_dpp v130, v130, v130 row_ror:8 row_mask:0xf bank_mask:0xc
	v_add_f32_dpp v130, v122, v122 row_ror:8 row_mask:0xf bank_mask:0x3
	v_add_f32_dpp v131, v131, v131 row_ror:8 row_mask:0xf bank_mask:0xc
	v_add_f32_dpp v12, v12, v12 row_ror:8 row_mask:0xf bank_mask:0xf bound_ctrl:1
	v_pk_fma_f32 v[6:7], v[24:25], v[12:13], v[48:49] op_sel_hi:[1,0,1] neg_lo:[1,0,0] neg_hi:[1,0,0]
	v_pk_fma_f32 v[8:9], v[26:27], v[12:13], v[50:51] op_sel_hi:[1,0,1] neg_lo:[1,0,0] neg_hi:[1,0,0]
	ds_read_b128 v[110:113], v10 offset:3328
	ds_read_b128 v[106:109], v10 offset:3072
	ds_read_b128 v[118:121], v10 offset:3840
	ds_read_b128 v[114:117], v10 offset:3584
	ds_read_b128 v[70:73], v11 offset:256
	v_fma_mix_f32 v12, v6, v36, v180 op_sel_hi:[0,1,0]
	v_fma_mix_f32 v12, v7, v36, v12 op_sel:[0,1,0] op_sel_hi:[0,1,0]
	v_fma_mix_f32 v12, v8, v37, v12 op_sel_hi:[0,1,0]
	v_fma_mix_f32 v12, v9, v37, v12 op_sel:[0,1,0] op_sel_hi:[0,1,0]
	v_fma_mix_f32 v52, v6, v22, v180 op_sel_hi:[0,1,0]
	v_fma_mix_f32 v52, v7, v22, v52 op_sel:[0,1,0] op_sel_hi:[0,1,0]
	v_add_f32_dpp v12, v12, v12 row_ror:1 row_mask:0xf bank_mask:0xf bound_ctrl:1
	v_fma_mix_f32 v52, v8, v23, v52 op_sel_hi:[0,1,0]
	v_fma_mix_f32 v52, v9, v23, v52 op_sel:[0,1,0] op_sel_hi:[0,1,0]
	v_add_f32_dpp v12, v12, v12 row_ror:2 row_mask:0xf bank_mask:0xf bound_ctrl:1
	v_pk_fma_f32 v[48:49], v[44:45], v[66:67], v[6:7] op_sel:[0,1,0]
	v_pk_fma_f32 v[50:51], v[46:47], v[66:67], v[8:9] op_sel:[0,1,0]
	v_add_f32_dpp v12, v12, v12 row_ror:4 row_mask:0xf bank_mask:0xf bound_ctrl:1
	v_add_f32_dpp v131, v123, v123 row_ror:8 row_mask:0xf bank_mask:0x3
	v_add_f32_dpp v132, v132, v132 row_ror:8 row_mask:0xf bank_mask:0xc
	v_add_f32_dpp v132, v124, v124 row_ror:8 row_mask:0xf bank_mask:0x3
	v_add_f32_dpp v12, v12, v12 row_ror:8 row_mask:0xf bank_mask:0xf bound_ctrl:1
	v_pk_fma_f32 v[6:7], v[40:41], v[12:13], v[48:49] op_sel_hi:[1,0,1] neg_lo:[1,0,0] neg_hi:[1,0,0]
	v_pk_fma_f32 v[8:9], v[42:43], v[12:13], v[50:51] op_sel_hi:[1,0,1] neg_lo:[1,0,0] neg_hi:[1,0,0]
	s_waitcnt lgkmcnt(1)
	ds_read_b128 v[20:23], v10 offset:4352
	ds_read_b128 v[28:31], v10 offset:4864
	ds_read_b128 v[24:27], v10 offset:4608
	v_fma_mix_f32 v12, v6, v88, v180 op_sel_hi:[0,1,0]
	v_fma_mix_f32 v12, v7, v88, v12 op_sel:[0,1,0] op_sel_hi:[0,1,0]
	v_fma_mix_f32 v12, v8, v89, v12 op_sel_hi:[0,1,0]
	v_fma_mix_f32 v12, v9, v89, v12 op_sel:[0,1,0] op_sel_hi:[0,1,0]
	v_fma_mix_f32 v53, v6, v38, v180 op_sel_hi:[0,1,0]
	v_fma_mix_f32 v53, v7, v38, v53 op_sel:[0,1,0] op_sel_hi:[0,1,0]
	v_add_f32_dpp v12, v12, v12 row_ror:1 row_mask:0xf bank_mask:0xf bound_ctrl:1
	v_fma_mix_f32 v53, v8, v39, v53 op_sel_hi:[0,1,0]
	v_fma_mix_f32 v53, v9, v39, v53 op_sel:[0,1,0] op_sel_hi:[0,1,0]
	v_add_f32_dpp v12, v12, v12 row_ror:2 row_mask:0xf bank_mask:0xf bound_ctrl:1
	v_pk_fma_f32 v[48:49], v[96:97], v[68:69], v[6:7] op_sel_hi:[1,0,1]
	v_pk_fma_f32 v[50:51], v[98:99], v[68:69], v[8:9] op_sel_hi:[1,0,1]
	v_add_f32_dpp v12, v12, v12 row_ror:4 row_mask:0xf bank_mask:0xf bound_ctrl:1
	v_add_f32_dpp v133, v133, v133 row_ror:8 row_mask:0xf bank_mask:0xc
	v_add_f32_dpp v133, v125, v125 row_ror:8 row_mask:0xf bank_mask:0x3
	v_add_f32_dpp v134, v134, v134 row_ror:8 row_mask:0xf bank_mask:0xc
	v_add_f32_dpp v12, v12, v12 row_ror:8 row_mask:0xf bank_mask:0xf bound_ctrl:1
	v_pk_fma_f32 v[6:7], v[92:93], v[12:13], v[48:49] op_sel_hi:[1,0,1] neg_lo:[1,0,0] neg_hi:[1,0,0]
	v_pk_fma_f32 v[8:9], v[94:95], v[12:13], v[50:51] op_sel_hi:[1,0,1] neg_lo:[1,0,0] neg_hi:[1,0,0]
	ds_read_b128 v[36:39], v10 offset:5376
	ds_read_b128 v[44:47], v10 offset:5888
	ds_read_b128 v[40:43], v10 offset:5632
	v_fma_mix_f32 v12, v6, v110, v180 op_sel_hi:[0,1,0]
	v_fma_mix_f32 v12, v7, v110, v12 op_sel:[0,1,0] op_sel_hi:[0,1,0]
	v_fma_mix_f32 v12, v8, v111, v12 op_sel_hi:[0,1,0]
	v_fma_mix_f32 v12, v9, v111, v12 op_sel:[0,1,0] op_sel_hi:[0,1,0]
	v_fma_mix_f32 v54, v6, v90, v180 op_sel_hi:[0,1,0]
	v_fma_mix_f32 v54, v7, v90, v54 op_sel:[0,1,0] op_sel_hi:[0,1,0]
	v_add_f32_dpp v12, v12, v12 row_ror:1 row_mask:0xf bank_mask:0xf bound_ctrl:1
	v_fma_mix_f32 v54, v8, v91, v54 op_sel_hi:[0,1,0]
	v_fma_mix_f32 v54, v9, v91, v54 op_sel:[0,1,0] op_sel_hi:[0,1,0]
	v_add_f32_dpp v12, v12, v12 row_ror:2 row_mask:0xf bank_mask:0xf bound_ctrl:1
	v_pk_fma_f32 v[48:49], v[118:119], v[68:69], v[6:7] op_sel:[0,1,0]
	v_pk_fma_f32 v[50:51], v[120:121], v[68:69], v[8:9] op_sel:[0,1,0]
	v_add_f32_dpp v12, v12, v12 row_ror:4 row_mask:0xf bank_mask:0xf bound_ctrl:1
	v_add_f32_dpp v134, v126, v126 row_ror:8 row_mask:0xf bank_mask:0x3
	v_add_f32_dpp v135, v135, v135 row_ror:8 row_mask:0xf bank_mask:0xc
	v_add_f32_dpp v135, v127, v127 row_ror:8 row_mask:0xf bank_mask:0x3
	v_add_f32_dpp v12, v12, v12 row_ror:8 row_mask:0xf bank_mask:0xf bound_ctrl:1
	v_pk_fma_f32 v[6:7], v[114:115], v[12:13], v[48:49] op_sel_hi:[1,0,1] neg_lo:[1,0,0] neg_hi:[1,0,0]
	v_pk_fma_f32 v[8:9], v[116:117], v[12:13], v[50:51] op_sel_hi:[1,0,1] neg_lo:[1,0,0] neg_hi:[1,0,0]
	v_pk_mul_f32 v[6:7], v[6:7], v[106:107]
	v_pk_mul_f32 v[8:9], v[8:9], v[108:109]
	s_waitcnt lgkmcnt(0)
	ds_read_b128 v[88:91], v10 offset:6400
	ds_read_b128 v[96:99], v10 offset:6912
	ds_read_b128 v[92:95], v10 offset:6656
	v_fma_mix_f32 v12, v6, v20, v180 op_sel_hi:[0,1,0]
	v_fma_mix_f32 v12, v7, v20, v12 op_sel:[0,1,0] op_sel_hi:[0,1,0]
	v_fma_mix_f32 v12, v8, v21, v12 op_sel_hi:[0,1,0]
	v_fma_mix_f32 v12, v9, v21, v12 op_sel:[0,1,0] op_sel_hi:[0,1,0]
	v_fma_mix_f32 v55, v6, v112, v180 op_sel_hi:[0,1,0]
	v_fma_mix_f32 v55, v7, v112, v55 op_sel:[0,1,0] op_sel_hi:[0,1,0]
	v_add_f32_dpp v12, v12, v12 row_ror:1 row_mask:0xf bank_mask:0xf bound_ctrl:1
	v_fma_mix_f32 v55, v8, v113, v55 op_sel_hi:[0,1,0]
	v_fma_mix_f32 v55, v9, v113, v55 op_sel:[0,1,0] op_sel_hi:[0,1,0]
	v_add_f32_dpp v12, v12, v12 row_ror:2 row_mask:0xf bank_mask:0xf bound_ctrl:1
	v_pk_fma_f32 v[48:49], v[28:29], v[70:71], v[6:7] op_sel_hi:[1,0,1]
	v_pk_fma_f32 v[50:51], v[30:31], v[70:71], v[8:9] op_sel_hi:[1,0,1]
	v_add_f32_dpp v12, v12, v12 row_ror:4 row_mask:0xf bank_mask:0xf bound_ctrl:1
	v_add_f32_dpp v136, v136, v136 row_ror:8 row_mask:0xf bank_mask:0xc
	v_add_f32_dpp v136, v128, v128 row_ror:8 row_mask:0xf bank_mask:0x3
	v_add_f32_dpp v12, v12, v12 row_ror:8 row_mask:0xf bank_mask:0xf bound_ctrl:1
	v_pk_fma_f32 v[6:7], v[24:25], v[12:13], v[48:49] op_sel_hi:[1,0,1] neg_lo:[1,0,0] neg_hi:[1,0,0]
	v_pk_fma_f32 v[8:9], v[26:27], v[12:13], v[50:51] op_sel_hi:[1,0,1] neg_lo:[1,0,0] neg_hi:[1,0,0]
	ds_read_b128 v[110:113], v10 offset:7424
	ds_read_b128 v[106:109], v10 offset:7168
	ds_read_b128 v[118:121], v10 offset:7936
	ds_read_b128 v[114:117], v10 offset:7680
	ds_read_b128 v[66:69], v11 offset:512
	v_fma_mix_f32 v12, v6, v36, v180 op_sel_hi:[0,1,0]
	v_fma_mix_f32 v12, v7, v36, v12 op_sel:[0,1,0] op_sel_hi:[0,1,0]
	v_fma_mix_f32 v12, v8, v37, v12 op_sel_hi:[0,1,0]
	v_fma_mix_f32 v12, v9, v37, v12 op_sel:[0,1,0] op_sel_hi:[0,1,0]
	v_fma_mix_f32 v56, v6, v22, v180 op_sel_hi:[0,1,0]
	v_fma_mix_f32 v56, v7, v22, v56 op_sel:[0,1,0] op_sel_hi:[0,1,0]
	v_add_f32_dpp v12, v12, v12 row_ror:1 row_mask:0xf bank_mask:0xf bound_ctrl:1
	v_fma_mix_f32 v56, v8, v23, v56 op_sel_hi:[0,1,0]
	v_fma_mix_f32 v56, v9, v23, v56 op_sel:[0,1,0] op_sel_hi:[0,1,0]
	v_add_f32_dpp v12, v12, v12 row_ror:2 row_mask:0xf bank_mask:0xf bound_ctrl:1
	v_pk_fma_f32 v[48:49], v[44:45], v[70:71], v[6:7] op_sel:[0,1,0]
	v_pk_fma_f32 v[50:51], v[46:47], v[70:71], v[8:9] op_sel:[0,1,0]
	v_add_f32_dpp v12, v12, v12 row_ror:4 row_mask:0xf bank_mask:0xf bound_ctrl:1
	v_add_f32_dpp v137, v137, v137 row_ror:8 row_mask:0xf bank_mask:0xc
	v_add_f32_dpp v137, v129, v129 row_ror:8 row_mask:0xf bank_mask:0x3
	v_add_f32_dpp v12, v12, v12 row_ror:8 row_mask:0xf bank_mask:0xf bound_ctrl:1
	v_pk_fma_f32 v[6:7], v[40:41], v[12:13], v[48:49] op_sel_hi:[1,0,1] neg_lo:[1,0,0] neg_hi:[1,0,0]
	v_pk_fma_f32 v[8:9], v[42:43], v[12:13], v[50:51] op_sel_hi:[1,0,1] neg_lo:[1,0,0] neg_hi:[1,0,0]
	s_waitcnt lgkmcnt(1)
	ds_read_b128 v[20:23], v10 offset:8448
	ds_read_b128 v[28:31], v10 offset:8960
	ds_read_b128 v[24:27], v10 offset:8704
	v_fma_mix_f32 v12, v6, v88, v180 op_sel_hi:[0,1,0]
	v_fma_mix_f32 v12, v7, v88, v12 op_sel:[0,1,0] op_sel_hi:[0,1,0]
	v_fma_mix_f32 v12, v8, v89, v12 op_sel_hi:[0,1,0]
	v_fma_mix_f32 v12, v9, v89, v12 op_sel:[0,1,0] op_sel_hi:[0,1,0]
	v_fma_mix_f32 v57, v6, v38, v180 op_sel_hi:[0,1,0]
	v_fma_mix_f32 v57, v7, v38, v57 op_sel:[0,1,0] op_sel_hi:[0,1,0]
	v_add_f32_dpp v12, v12, v12 row_ror:1 row_mask:0xf bank_mask:0xf bound_ctrl:1
	v_fma_mix_f32 v57, v8, v39, v57 op_sel_hi:[0,1,0]
	v_fma_mix_f32 v57, v9, v39, v57 op_sel:[0,1,0] op_sel_hi:[0,1,0]
	v_add_f32_dpp v12, v12, v12 row_ror:2 row_mask:0xf bank_mask:0xf bound_ctrl:1
	v_pk_fma_f32 v[48:49], v[96:97], v[72:73], v[6:7] op_sel_hi:[1,0,1]
	v_pk_fma_f32 v[50:51], v[98:99], v[72:73], v[8:9] op_sel_hi:[1,0,1]
	v_add_f32_dpp v12, v12, v12 row_ror:4 row_mask:0xf bank_mask:0xf bound_ctrl:1
	v_add_f32_dpp v134, v134, v134 row_ror:4 row_mask:0xf bank_mask:0xa
	v_add_f32_dpp v134, v130, v130 row_ror:12 row_mask:0xf bank_mask:0x5
	v_add_f32_dpp v135, v135, v135 row_ror:4 row_mask:0xf bank_mask:0xa
	v_add_f32_dpp v12, v12, v12 row_ror:8 row_mask:0xf bank_mask:0xf bound_ctrl:1
	v_pk_fma_f32 v[6:7], v[92:93], v[12:13], v[48:49] op_sel_hi:[1,0,1] neg_lo:[1,0,0] neg_hi:[1,0,0]
	v_pk_fma_f32 v[8:9], v[94:95], v[12:13], v[50:51] op_sel_hi:[1,0,1] neg_lo:[1,0,0] neg_hi:[1,0,0]
	ds_read_b128 v[36:39], v10 offset:9472
	ds_read_b128 v[44:47], v10 offset:9984
	ds_read_b128 v[40:43], v10 offset:9728
	v_fma_mix_f32 v12, v6, v110, v180 op_sel_hi:[0,1,0]
	v_fma_mix_f32 v12, v7, v110, v12 op_sel:[0,1,0] op_sel_hi:[0,1,0]
	v_fma_mix_f32 v12, v8, v111, v12 op_sel_hi:[0,1,0]
	v_fma_mix_f32 v12, v9, v111, v12 op_sel:[0,1,0] op_sel_hi:[0,1,0]
	v_fma_mix_f32 v81, v6, v90, v180 op_sel_hi:[0,1,0]
	v_fma_mix_f32 v81, v7, v90, v81 op_sel:[0,1,0] op_sel_hi:[0,1,0]
	v_add_f32_dpp v12, v12, v12 row_ror:1 row_mask:0xf bank_mask:0xf bound_ctrl:1
	v_fma_mix_f32 v81, v8, v91, v81 op_sel_hi:[0,1,0]
	v_fma_mix_f32 v81, v9, v91, v81 op_sel:[0,1,0] op_sel_hi:[0,1,0]
	v_add_f32_dpp v12, v12, v12 row_ror:2 row_mask:0xf bank_mask:0xf bound_ctrl:1
	v_pk_fma_f32 v[48:49], v[118:119], v[72:73], v[6:7] op_sel:[0,1,0]
	v_pk_fma_f32 v[50:51], v[120:121], v[72:73], v[8:9] op_sel:[0,1,0]
	v_add_f32_dpp v12, v12, v12 row_ror:4 row_mask:0xf bank_mask:0xf bound_ctrl:1
	v_add_f32_dpp v135, v131, v131 row_ror:12 row_mask:0xf bank_mask:0x5
	v_add_f32_dpp v136, v136, v136 row_ror:4 row_mask:0xf bank_mask:0xa
	v_add_f32_dpp v136, v132, v132 row_ror:12 row_mask:0xf bank_mask:0x5
	v_add_f32_dpp v12, v12, v12 row_ror:8 row_mask:0xf bank_mask:0xf bound_ctrl:1
	v_pk_fma_f32 v[6:7], v[114:115], v[12:13], v[48:49] op_sel_hi:[1,0,1] neg_lo:[1,0,0] neg_hi:[1,0,0]
	v_pk_fma_f32 v[8:9], v[116:117], v[12:13], v[50:51] op_sel_hi:[1,0,1] neg_lo:[1,0,0] neg_hi:[1,0,0]
	v_pk_mul_f32 v[6:7], v[6:7], v[106:107]
	v_pk_mul_f32 v[8:9], v[8:9], v[108:109]
	s_waitcnt lgkmcnt(0)
	ds_read_b128 v[88:91], v10 offset:10496
	ds_read_b128 v[96:99], v10 offset:11008
	ds_read_b128 v[92:95], v10 offset:10752
	v_fma_mix_f32 v12, v6, v20, v180 op_sel_hi:[0,1,0]
	v_fma_mix_f32 v12, v7, v20, v12 op_sel:[0,1,0] op_sel_hi:[0,1,0]
	v_fma_mix_f32 v12, v8, v21, v12 op_sel_hi:[0,1,0]
	v_fma_mix_f32 v12, v9, v21, v12 op_sel:[0,1,0] op_sel_hi:[0,1,0]
	v_fma_mix_f32 v82, v6, v112, v180 op_sel_hi:[0,1,0]
	v_fma_mix_f32 v82, v7, v112, v82 op_sel:[0,1,0] op_sel_hi:[0,1,0]
	v_add_f32_dpp v12, v12, v12 row_ror:1 row_mask:0xf bank_mask:0xf bound_ctrl:1
	v_fma_mix_f32 v82, v8, v113, v82 op_sel_hi:[0,1,0]
	v_fma_mix_f32 v82, v9, v113, v82 op_sel:[0,1,0] op_sel_hi:[0,1,0]
	v_add_f32_dpp v12, v12, v12 row_ror:2 row_mask:0xf bank_mask:0xf bound_ctrl:1
	v_pk_fma_f32 v[48:49], v[28:29], v[66:67], v[6:7] op_sel_hi:[1,0,1]
	v_pk_fma_f32 v[50:51], v[30:31], v[66:67], v[8:9] op_sel_hi:[1,0,1]
	v_add_f32_dpp v12, v12, v12 row_ror:4 row_mask:0xf bank_mask:0xf bound_ctrl:1
	v_add_f32_dpp v137, v137, v137 row_ror:4 row_mask:0xf bank_mask:0xa
	v_add_f32_dpp v137, v133, v133 row_ror:12 row_mask:0xf bank_mask:0x5
	v_add_f32_dpp v12, v12, v12 row_ror:8 row_mask:0xf bank_mask:0xf bound_ctrl:1
	v_pk_fma_f32 v[6:7], v[24:25], v[12:13], v[48:49] op_sel_hi:[1,0,1] neg_lo:[1,0,0] neg_hi:[1,0,0]
	v_pk_fma_f32 v[8:9], v[26:27], v[12:13], v[50:51] op_sel_hi:[1,0,1] neg_lo:[1,0,0] neg_hi:[1,0,0]
	ds_read_b128 v[110:113], v10 offset:11520
	ds_read_b128 v[106:109], v10 offset:11264
	ds_read_b128 v[118:121], v10 offset:12032
	ds_read_b128 v[114:117], v10 offset:11776
	ds_read_b128 v[70:73], v11 offset:768
	v_fma_mix_f32 v12, v6, v36, v180 op_sel_hi:[0,1,0]
	v_fma_mix_f32 v12, v7, v36, v12 op_sel:[0,1,0] op_sel_hi:[0,1,0]
	v_fma_mix_f32 v12, v8, v37, v12 op_sel_hi:[0,1,0]
	v_fma_mix_f32 v12, v9, v37, v12 op_sel:[0,1,0] op_sel_hi:[0,1,0]
	v_fma_mix_f32 v83, v6, v22, v180 op_sel_hi:[0,1,0]
	v_fma_mix_f32 v83, v7, v22, v83 op_sel:[0,1,0] op_sel_hi:[0,1,0]
	v_add_f32_dpp v12, v12, v12 row_ror:1 row_mask:0xf bank_mask:0xf bound_ctrl:1
	v_fma_mix_f32 v83, v8, v23, v83 op_sel_hi:[0,1,0]
	v_fma_mix_f32 v83, v9, v23, v83 op_sel:[0,1,0] op_sel_hi:[0,1,0]
	v_add_f32_dpp v12, v12, v12 row_ror:2 row_mask:0xf bank_mask:0xf bound_ctrl:1
	v_pk_fma_f32 v[48:49], v[44:45], v[66:67], v[6:7] op_sel:[0,1,0]
	v_pk_fma_f32 v[50:51], v[46:47], v[66:67], v[8:9] op_sel:[0,1,0]
	v_add_f32_dpp v12, v12, v12 row_ror:4 row_mask:0xf bank_mask:0xf bound_ctrl:1
	v_cndmask_b32_e64 v62, v136, v134, s[38:39]
	v_cndmask_b32_e64 v63, v134, v136, s[38:39]
	v_add_f32_dpp v12, v12, v12 row_ror:8 row_mask:0xf bank_mask:0xf bound_ctrl:1
	v_pk_fma_f32 v[6:7], v[40:41], v[12:13], v[48:49] op_sel_hi:[1,0,1] neg_lo:[1,0,0] neg_hi:[1,0,0]
	v_pk_fma_f32 v[8:9], v[42:43], v[12:13], v[50:51] op_sel_hi:[1,0,1] neg_lo:[1,0,0] neg_hi:[1,0,0]
	s_waitcnt lgkmcnt(1)
	ds_read_b128 v[20:23], v10 offset:12544
	ds_read_b128 v[28:31], v10 offset:13056
	ds_read_b128 v[24:27], v10 offset:12800
	v_fma_mix_f32 v12, v6, v88, v180 op_sel_hi:[0,1,0]
	v_fma_mix_f32 v12, v7, v88, v12 op_sel:[0,1,0] op_sel_hi:[0,1,0]
	v_fma_mix_f32 v12, v8, v89, v12 op_sel_hi:[0,1,0]
	v_fma_mix_f32 v12, v9, v89, v12 op_sel:[0,1,0] op_sel_hi:[0,1,0]
	v_fma_mix_f32 v100, v6, v38, v180 op_sel_hi:[0,1,0]
	v_fma_mix_f32 v100, v7, v38, v100 op_sel:[0,1,0] op_sel_hi:[0,1,0]
	v_add_f32_dpp v12, v12, v12 row_ror:1 row_mask:0xf bank_mask:0xf bound_ctrl:1
	v_fma_mix_f32 v100, v8, v39, v100 op_sel_hi:[0,1,0]
	v_fma_mix_f32 v100, v9, v39, v100 op_sel:[0,1,0] op_sel_hi:[0,1,0]
	v_add_f32_dpp v12, v12, v12 row_ror:2 row_mask:0xf bank_mask:0xf bound_ctrl:1
	v_pk_fma_f32 v[48:49], v[96:97], v[68:69], v[6:7] op_sel_hi:[1,0,1]
	v_pk_fma_f32 v[50:51], v[98:99], v[68:69], v[8:9] op_sel_hi:[1,0,1]
	v_add_f32_dpp v12, v12, v12 row_ror:4 row_mask:0xf bank_mask:0xf bound_ctrl:1
	v_cndmask_b32_e64 v64, v137, v135, s[38:39]
	v_cndmask_b32_e64 v65, v135, v137, s[38:39]
	v_add_f32_dpp v12, v12, v12 row_ror:8 row_mask:0xf bank_mask:0xf bound_ctrl:1
	v_pk_fma_f32 v[6:7], v[92:93], v[12:13], v[48:49] op_sel_hi:[1,0,1] neg_lo:[1,0,0] neg_hi:[1,0,0]
	v_pk_fma_f32 v[8:9], v[94:95], v[12:13], v[50:51] op_sel_hi:[1,0,1] neg_lo:[1,0,0] neg_hi:[1,0,0]
	ds_read_b128 v[36:39], v10 offset:13568
	ds_read_b128 v[44:47], v10 offset:14080
	ds_read_b128 v[40:43], v10 offset:13824
	v_fma_mix_f32 v12, v6, v110, v180 op_sel_hi:[0,1,0]
	v_fma_mix_f32 v12, v7, v110, v12 op_sel:[0,1,0] op_sel_hi:[0,1,0]
	v_fma_mix_f32 v12, v8, v111, v12 op_sel_hi:[0,1,0]
	v_fma_mix_f32 v12, v9, v111, v12 op_sel:[0,1,0] op_sel_hi:[0,1,0]
	v_fma_mix_f32 v101, v6, v90, v180 op_sel_hi:[0,1,0]
	v_fma_mix_f32 v101, v7, v90, v101 op_sel:[0,1,0] op_sel_hi:[0,1,0]
	v_add_f32_dpp v12, v12, v12 row_ror:1 row_mask:0xf bank_mask:0xf bound_ctrl:1
	v_fma_mix_f32 v101, v8, v91, v101 op_sel_hi:[0,1,0]
	v_fma_mix_f32 v101, v9, v91, v101 op_sel:[0,1,0] op_sel_hi:[0,1,0]
	v_add_f32_dpp v12, v12, v12 row_ror:2 row_mask:0xf bank_mask:0xf bound_ctrl:1
	v_pk_fma_f32 v[48:49], v[118:119], v[68:69], v[6:7] op_sel:[0,1,0]
	v_pk_fma_f32 v[50:51], v[120:121], v[68:69], v[8:9] op_sel:[0,1,0]
	v_add_f32_dpp v12, v12, v12 row_ror:4 row_mask:0xf bank_mask:0xf bound_ctrl:1
	v_add_f32_dpp v62, v63, v62 quad_perm:[2,3,0,1] row_mask:0xf bank_mask:0xf bound_ctrl:1
	v_add_f32_dpp v63, v65, v64 quad_perm:[2,3,0,1] row_mask:0xf bank_mask:0xf bound_ctrl:1
	v_add_f32_dpp v12, v12, v12 row_ror:8 row_mask:0xf bank_mask:0xf bound_ctrl:1
	v_pk_fma_f32 v[6:7], v[114:115], v[12:13], v[48:49] op_sel_hi:[1,0,1] neg_lo:[1,0,0] neg_hi:[1,0,0]
	v_pk_fma_f32 v[8:9], v[116:117], v[12:13], v[50:51] op_sel_hi:[1,0,1] neg_lo:[1,0,0] neg_hi:[1,0,0]
	v_pk_mul_f32 v[6:7], v[6:7], v[106:107]
	v_pk_mul_f32 v[8:9], v[8:9], v[108:109]
	s_waitcnt lgkmcnt(0)
	ds_read_b128 v[88:91], v10 offset:14592
	ds_read_b128 v[96:99], v10 offset:15104
	ds_read_b128 v[92:95], v10 offset:14848
	v_fma_mix_f32 v12, v6, v20, v180 op_sel_hi:[0,1,0]
	v_fma_mix_f32 v12, v7, v20, v12 op_sel:[0,1,0] op_sel_hi:[0,1,0]
	v_fma_mix_f32 v12, v8, v21, v12 op_sel_hi:[0,1,0]
	v_fma_mix_f32 v12, v9, v21, v12 op_sel:[0,1,0] op_sel_hi:[0,1,0]
	v_fma_mix_f32 v102, v6, v112, v180 op_sel_hi:[0,1,0]
	v_fma_mix_f32 v102, v7, v112, v102 op_sel:[0,1,0] op_sel_hi:[0,1,0]
	v_add_f32_dpp v12, v12, v12 row_ror:1 row_mask:0xf bank_mask:0xf bound_ctrl:1
	v_fma_mix_f32 v102, v8, v113, v102 op_sel_hi:[0,1,0]
	v_fma_mix_f32 v102, v9, v113, v102 op_sel:[0,1,0] op_sel_hi:[0,1,0]
	v_add_f32_dpp v12, v12, v12 row_ror:2 row_mask:0xf bank_mask:0xf bound_ctrl:1
	v_pk_fma_f32 v[48:49], v[28:29], v[70:71], v[6:7] op_sel_hi:[1,0,1]
	v_pk_fma_f32 v[50:51], v[30:31], v[70:71], v[8:9] op_sel_hi:[1,0,1]
	v_add_f32_dpp v12, v12, v12 row_ror:4 row_mask:0xf bank_mask:0xf bound_ctrl:1
	v_cndmask_b32_e64 v65, v63, v62, s[40:41]
	v_cndmask_b32_e64 v62, v62, v63, s[40:41]
	v_add_f32_dpp v12, v12, v12 row_ror:8 row_mask:0xf bank_mask:0xf bound_ctrl:1
	v_pk_fma_f32 v[6:7], v[24:25], v[12:13], v[48:49] op_sel_hi:[1,0,1] neg_lo:[1,0,0] neg_hi:[1,0,0]
	v_pk_fma_f32 v[8:9], v[26:27], v[12:13], v[50:51] op_sel_hi:[1,0,1] neg_lo:[1,0,0] neg_hi:[1,0,0]
	ds_read_b128 v[110:113], v10 offset:15616
	ds_read_b128 v[106:109], v10 offset:15360
	ds_read_b128 v[118:121], v10 offset:16128
	ds_read_b128 v[114:117], v10 offset:15872
	ds_read_b128 v[66:69], v11 offset:1024
	v_fma_mix_f32 v12, v6, v36, v180 op_sel_hi:[0,1,0]
	v_fma_mix_f32 v12, v7, v36, v12 op_sel:[0,1,0] op_sel_hi:[0,1,0]
	v_fma_mix_f32 v12, v8, v37, v12 op_sel_hi:[0,1,0]
	v_fma_mix_f32 v12, v9, v37, v12 op_sel:[0,1,0] op_sel_hi:[0,1,0]
	v_fma_mix_f32 v103, v6, v22, v180 op_sel_hi:[0,1,0]
	v_fma_mix_f32 v103, v7, v22, v103 op_sel:[0,1,0] op_sel_hi:[0,1,0]
	v_add_f32_dpp v12, v12, v12 row_ror:1 row_mask:0xf bank_mask:0xf bound_ctrl:1
	v_fma_mix_f32 v103, v8, v23, v103 op_sel_hi:[0,1,0]
	v_fma_mix_f32 v103, v9, v23, v103 op_sel:[0,1,0] op_sel_hi:[0,1,0]
	v_add_f32_dpp v12, v12, v12 row_ror:2 row_mask:0xf bank_mask:0xf bound_ctrl:1
	v_pk_fma_f32 v[48:49], v[44:45], v[70:71], v[6:7] op_sel:[0,1,0]
	v_pk_fma_f32 v[50:51], v[46:47], v[70:71], v[8:9] op_sel:[0,1,0]
	v_add_f32_dpp v12, v12, v12 row_ror:4 row_mask:0xf bank_mask:0xf bound_ctrl:1
	v_add_f32_dpp v62, v62, v65 quad_perm:[1,0,3,2] row_mask:0xf bank_mask:0xf bound_ctrl:1
	v_cvt_pk_bf16_f32 v62, v62, v62
	v_add_f32_dpp v12, v12, v12 row_ror:8 row_mask:0xf bank_mask:0xf bound_ctrl:1
	v_pk_fma_f32 v[6:7], v[40:41], v[12:13], v[48:49] op_sel_hi:[1,0,1] neg_lo:[1,0,0] neg_hi:[1,0,0]
	v_pk_fma_f32 v[8:9], v[42:43], v[12:13], v[50:51] op_sel_hi:[1,0,1] neg_lo:[1,0,0] neg_hi:[1,0,0]
	s_waitcnt lgkmcnt(1)
	ds_read_b128 v[20:23], v10 offset:16640
	ds_read_b128 v[28:31], v10 offset:17152
	ds_read_b128 v[24:27], v10 offset:16896
	v_fma_mix_f32 v12, v6, v88, v180 op_sel_hi:[0,1,0]
	v_fma_mix_f32 v12, v7, v88, v12 op_sel:[0,1,0] op_sel_hi:[0,1,0]
	v_fma_mix_f32 v12, v8, v89, v12 op_sel_hi:[0,1,0]
	v_fma_mix_f32 v12, v9, v89, v12 op_sel:[0,1,0] op_sel_hi:[0,1,0]
	v_fma_mix_f32 v104, v6, v38, v180 op_sel_hi:[0,1,0]
	v_fma_mix_f32 v104, v7, v38, v104 op_sel:[0,1,0] op_sel_hi:[0,1,0]
	v_add_f32_dpp v12, v12, v12 row_ror:1 row_mask:0xf bank_mask:0xf bound_ctrl:1
	v_fma_mix_f32 v104, v8, v39, v104 op_sel_hi:[0,1,0]
	v_fma_mix_f32 v104, v9, v39, v104 op_sel:[0,1,0] op_sel_hi:[0,1,0]
	v_add_f32_dpp v12, v12, v12 row_ror:2 row_mask:0xf bank_mask:0xf bound_ctrl:1
	v_pk_fma_f32 v[48:49], v[96:97], v[72:73], v[6:7] op_sel_hi:[1,0,1]
	v_pk_fma_f32 v[50:51], v[98:99], v[72:73], v[8:9] op_sel_hi:[1,0,1]
	v_add_f32_dpp v12, v12, v12 row_ror:4 row_mask:0xf bank_mask:0xf bound_ctrl:1
	s_mov_b64 exec, s[100:101]
	global_store_short v[170:171], v62, off
	s_mov_b64 exec, -1
	v_add_f32_dpp v12, v12, v12 row_ror:8 row_mask:0xf bank_mask:0xf bound_ctrl:1
	v_pk_fma_f32 v[6:7], v[92:93], v[12:13], v[48:49] op_sel_hi:[1,0,1] neg_lo:[1,0,0] neg_hi:[1,0,0]
	v_pk_fma_f32 v[8:9], v[94:95], v[12:13], v[50:51] op_sel_hi:[1,0,1] neg_lo:[1,0,0] neg_hi:[1,0,0]
	ds_read_b128 v[36:39], v10 offset:17664
	ds_read_b128 v[44:47], v10 offset:18176
	ds_read_b128 v[40:43], v10 offset:17920
	v_fma_mix_f32 v12, v6, v110, v180 op_sel_hi:[0,1,0]
	v_fma_mix_f32 v12, v7, v110, v12 op_sel:[0,1,0] op_sel_hi:[0,1,0]
	v_fma_mix_f32 v12, v8, v111, v12 op_sel_hi:[0,1,0]
	v_fma_mix_f32 v12, v9, v111, v12 op_sel:[0,1,0] op_sel_hi:[0,1,0]
	v_fma_mix_f32 v105, v6, v90, v180 op_sel_hi:[0,1,0]
	v_fma_mix_f32 v105, v7, v90, v105 op_sel:[0,1,0] op_sel_hi:[0,1,0]
	v_add_f32_dpp v12, v12, v12 row_ror:1 row_mask:0xf bank_mask:0xf bound_ctrl:1
	v_fma_mix_f32 v105, v8, v91, v105 op_sel_hi:[0,1,0]
	v_fma_mix_f32 v105, v9, v91, v105 op_sel:[0,1,0] op_sel_hi:[0,1,0]
	v_add_f32_dpp v12, v12, v12 row_ror:2 row_mask:0xf bank_mask:0xf bound_ctrl:1
	v_pk_fma_f32 v[48:49], v[118:119], v[72:73], v[6:7] op_sel:[0,1,0]
	v_pk_fma_f32 v[50:51], v[120:121], v[72:73], v[8:9] op_sel:[0,1,0]
	v_add_f32_dpp v12, v12, v12 row_ror:4 row_mask:0xf bank_mask:0xf bound_ctrl:1
	s_nop 1
	v_add_f32_dpp v12, v12, v12 row_ror:8 row_mask:0xf bank_mask:0xf bound_ctrl:1
	v_pk_fma_f32 v[6:7], v[114:115], v[12:13], v[48:49] op_sel_hi:[1,0,1] neg_lo:[1,0,0] neg_hi:[1,0,0]
	v_pk_fma_f32 v[8:9], v[116:117], v[12:13], v[50:51] op_sel_hi:[1,0,1] neg_lo:[1,0,0] neg_hi:[1,0,0]
	v_pk_mul_f32 v[6:7], v[6:7], v[106:107]
	v_pk_mul_f32 v[8:9], v[8:9], v[108:109]
	s_waitcnt lgkmcnt(0)
	ds_read_b128 v[88:91], v10 offset:18688
	ds_read_b128 v[96:99], v10 offset:19200
	ds_read_b128 v[92:95], v10 offset:18944
	v_fma_mix_f32 v12, v6, v20, v180 op_sel_hi:[0,1,0]
	v_fma_mix_f32 v12, v7, v20, v12 op_sel:[0,1,0] op_sel_hi:[0,1,0]
	v_fma_mix_f32 v12, v8, v21, v12 op_sel_hi:[0,1,0]
	v_fma_mix_f32 v12, v9, v21, v12 op_sel:[0,1,0] op_sel_hi:[0,1,0]
	v_fma_mix_f32 v61, v6, v112, v180 op_sel_hi:[0,1,0]
	v_fma_mix_f32 v61, v7, v112, v61 op_sel:[0,1,0] op_sel_hi:[0,1,0]
	v_add_f32_dpp v12, v12, v12 row_ror:1 row_mask:0xf bank_mask:0xf bound_ctrl:1
	v_fma_mix_f32 v61, v8, v113, v61 op_sel_hi:[0,1,0]
	v_fma_mix_f32 v61, v9, v113, v61 op_sel:[0,1,0] op_sel_hi:[0,1,0]
	v_add_f32_dpp v12, v12, v12 row_ror:2 row_mask:0xf bank_mask:0xf bound_ctrl:1
	v_pk_fma_f32 v[48:49], v[28:29], v[66:67], v[6:7] op_sel_hi:[1,0,1]
	v_pk_fma_f32 v[50:51], v[30:31], v[66:67], v[8:9] op_sel_hi:[1,0,1]
	v_add_f32_dpp v12, v12, v12 row_ror:4 row_mask:0xf bank_mask:0xf bound_ctrl:1
	s_nop 1
	v_add_f32_dpp v12, v12, v12 row_ror:8 row_mask:0xf bank_mask:0xf bound_ctrl:1
	v_pk_fma_f32 v[6:7], v[24:25], v[12:13], v[48:49] op_sel_hi:[1,0,1] neg_lo:[1,0,0] neg_hi:[1,0,0]
	v_pk_fma_f32 v[8:9], v[26:27], v[12:13], v[50:51] op_sel_hi:[1,0,1] neg_lo:[1,0,0] neg_hi:[1,0,0]
	ds_read_b128 v[110:113], v10 offset:19712
	ds_read_b128 v[106:109], v10 offset:19456
	ds_read_b128 v[118:121], v10 offset:20224
	ds_read_b128 v[114:117], v10 offset:19968
	ds_read_b128 v[70:73], v11 offset:1280
	v_fma_mix_f32 v12, v6, v36, v180 op_sel_hi:[0,1,0]
	v_fma_mix_f32 v12, v7, v36, v12 op_sel:[0,1,0] op_sel_hi:[0,1,0]
	v_fma_mix_f32 v12, v8, v37, v12 op_sel_hi:[0,1,0]
	v_fma_mix_f32 v12, v9, v37, v12 op_sel:[0,1,0] op_sel_hi:[0,1,0]
	v_fma_mix_f32 v122, v6, v22, v180 op_sel_hi:[0,1,0]
	v_fma_mix_f32 v122, v7, v22, v122 op_sel:[0,1,0] op_sel_hi:[0,1,0]
	v_add_f32_dpp v12, v12, v12 row_ror:1 row_mask:0xf bank_mask:0xf bound_ctrl:1
	v_fma_mix_f32 v122, v8, v23, v122 op_sel_hi:[0,1,0]
	v_fma_mix_f32 v122, v9, v23, v122 op_sel:[0,1,0] op_sel_hi:[0,1,0]
	v_add_f32_dpp v12, v12, v12 row_ror:2 row_mask:0xf bank_mask:0xf bound_ctrl:1
	v_pk_fma_f32 v[48:49], v[44:45], v[66:67], v[6:7] op_sel:[0,1,0]
	v_pk_fma_f32 v[50:51], v[46:47], v[66:67], v[8:9] op_sel:[0,1,0]
	v_add_f32_dpp v12, v12, v12 row_ror:4 row_mask:0xf bank_mask:0xf bound_ctrl:1
	v_add_f32_dpp v83, v83, v83 row_ror:8 row_mask:0xf bank_mask:0xc
	v_add_f32_dpp v83, v52, v52 row_ror:8 row_mask:0xf bank_mask:0x3
	v_add_f32_dpp v100, v100, v100 row_ror:8 row_mask:0xf bank_mask:0xc
	v_add_f32_dpp v12, v12, v12 row_ror:8 row_mask:0xf bank_mask:0xf bound_ctrl:1
	v_pk_fma_f32 v[6:7], v[40:41], v[12:13], v[48:49] op_sel_hi:[1,0,1] neg_lo:[1,0,0] neg_hi:[1,0,0]
	v_pk_fma_f32 v[8:9], v[42:43], v[12:13], v[50:51] op_sel_hi:[1,0,1] neg_lo:[1,0,0] neg_hi:[1,0,0]
	s_waitcnt lgkmcnt(1)
	ds_read_b128 v[20:23], v10 offset:20736
	ds_read_b128 v[28:31], v10 offset:21248
	ds_read_b128 v[24:27], v10 offset:20992
	v_fma_mix_f32 v12, v6, v88, v180 op_sel_hi:[0,1,0]
	v_fma_mix_f32 v12, v7, v88, v12 op_sel:[0,1,0] op_sel_hi:[0,1,0]
	v_fma_mix_f32 v12, v8, v89, v12 op_sel_hi:[0,1,0]
	v_fma_mix_f32 v12, v9, v89, v12 op_sel:[0,1,0] op_sel_hi:[0,1,0]
	v_fma_mix_f32 v123, v6, v38, v180 op_sel_hi:[0,1,0]
	v_fma_mix_f32 v123, v7, v38, v123 op_sel:[0,1,0] op_sel_hi:[0,1,0]
	v_add_f32_dpp v12, v12, v12 row_ror:1 row_mask:0xf bank_mask:0xf bound_ctrl:1
	v_fma_mix_f32 v123, v8, v39, v123 op_sel_hi:[0,1,0]
	v_fma_mix_f32 v123, v9, v39, v123 op_sel:[0,1,0] op_sel_hi:[0,1,0]
	v_add_f32_dpp v12, v12, v12 row_ror:2 row_mask:0xf bank_mask:0xf bound_ctrl:1
	v_pk_fma_f32 v[48:49], v[96:97], v[68:69], v[6:7] op_sel_hi:[1,0,1]
	v_pk_fma_f32 v[50:51], v[98:99], v[68:69], v[8:9] op_sel_hi:[1,0,1]
	v_add_f32_dpp v12, v12, v12 row_ror:4 row_mask:0xf bank_mask:0xf bound_ctrl:1
	v_add_f32_dpp v100, v53, v53 row_ror:8 row_mask:0xf bank_mask:0x3
	v_add_f32_dpp v101, v101, v101 row_ror:8 row_mask:0xf bank_mask:0xc
	v_add_f32_dpp v101, v54, v54 row_ror:8 row_mask:0xf bank_mask:0x3
	v_add_f32_dpp v12, v12, v12 row_ror:8 row_mask:0xf bank_mask:0xf bound_ctrl:1
	v_pk_fma_f32 v[6:7], v[92:93], v[12:13], v[48:49] op_sel_hi:[1,0,1] neg_lo:[1,0,0] neg_hi:[1,0,0]
	v_pk_fma_f32 v[8:9], v[94:95], v[12:13], v[50:51] op_sel_hi:[1,0,1] neg_lo:[1,0,0] neg_hi:[1,0,0]
	ds_read_b128 v[36:39], v10 offset:21760
	ds_read_b128 v[44:47], v10 offset:22272
	ds_read_b128 v[40:43], v10 offset:22016
	v_fma_mix_f32 v12, v6, v110, v180 op_sel_hi:[0,1,0]
	v_fma_mix_f32 v12, v7, v110, v12 op_sel:[0,1,0] op_sel_hi:[0,1,0]
	v_fma_mix_f32 v12, v8, v111, v12 op_sel_hi:[0,1,0]
	v_fma_mix_f32 v12, v9, v111, v12 op_sel:[0,1,0] op_sel_hi:[0,1,0]
	v_fma_mix_f32 v124, v6, v90, v180 op_sel_hi:[0,1,0]
	v_fma_mix_f32 v124, v7, v90, v124 op_sel:[0,1,0] op_sel_hi:[0,1,0]
	v_add_f32_dpp v12, v12, v12 row_ror:1 row_mask:0xf bank_mask:0xf bound_ctrl:1
	v_fma_mix_f32 v124, v8, v91, v124 op_sel_hi:[0,1,0]
	v_fma_mix_f32 v124, v9, v91, v124 op_sel:[0,1,0] op_sel_hi:[0,1,0]
	v_add_f32_dpp v12, v12, v12 row_ror:2 row_mask:0xf bank_mask:0xf bound_ctrl:1
	v_pk_fma_f32 v[48:49], v[118:119], v[68:69], v[6:7] op_sel:[0,1,0]
	v_pk_fma_f32 v[50:51], v[120:121], v[68:69], v[8:9] op_sel:[0,1,0]
	v_add_f32_dpp v12, v12, v12 row_ror:4 row_mask:0xf bank_mask:0xf bound_ctrl:1
	v_add_f32_dpp v102, v102, v102 row_ror:8 row_mask:0xf bank_mask:0xc
	v_add_f32_dpp v102, v55, v55 row_ror:8 row_mask:0xf bank_mask:0x3
	v_add_f32_dpp v103, v103, v103 row_ror:8 row_mask:0xf bank_mask:0xc
	v_add_f32_dpp v12, v12, v12 row_ror:8 row_mask:0xf bank_mask:0xf bound_ctrl:1
	v_pk_fma_f32 v[6:7], v[114:115], v[12:13], v[48:49] op_sel_hi:[1,0,1] neg_lo:[1,0,0] neg_hi:[1,0,0]
	v_pk_fma_f32 v[8:9], v[116:117], v[12:13], v[50:51] op_sel_hi:[1,0,1] neg_lo:[1,0,0] neg_hi:[1,0,0]
	v_pk_mul_f32 v[6:7], v[6:7], v[106:107]
	v_pk_mul_f32 v[8:9], v[8:9], v[108:109]
	s_waitcnt lgkmcnt(0)
	ds_read_b128 v[88:91], v10 offset:22784
	ds_read_b128 v[96:99], v10 offset:23296
	ds_read_b128 v[92:95], v10 offset:23040
	v_fma_mix_f32 v12, v6, v20, v180 op_sel_hi:[0,1,0]
	v_fma_mix_f32 v12, v7, v20, v12 op_sel:[0,1,0] op_sel_hi:[0,1,0]
	v_fma_mix_f32 v12, v8, v21, v12 op_sel_hi:[0,1,0]
	v_fma_mix_f32 v12, v9, v21, v12 op_sel:[0,1,0] op_sel_hi:[0,1,0]
	v_fma_mix_f32 v125, v6, v112, v180 op_sel_hi:[0,1,0]
	v_fma_mix_f32 v125, v7, v112, v125 op_sel:[0,1,0] op_sel_hi:[0,1,0]
	v_add_f32_dpp v12, v12, v12 row_ror:1 row_mask:0xf bank_mask:0xf bound_ctrl:1
	v_fma_mix_f32 v125, v8, v113, v125 op_sel_hi:[0,1,0]
	v_fma_mix_f32 v125, v9, v113, v125 op_sel:[0,1,0] op_sel_hi:[0,1,0]
	v_add_f32_dpp v12, v12, v12 row_ror:2 row_mask:0xf bank_mask:0xf bound_ctrl:1
	v_pk_fma_f32 v[48:49], v[28:29], v[70:71], v[6:7] op_sel_hi:[1,0,1]
	v_pk_fma_f32 v[50:51], v[30:31], v[70:71], v[8:9] op_sel_hi:[1,0,1]
	v_add_f32_dpp v12, v12, v12 row_ror:4 row_mask:0xf bank_mask:0xf bound_ctrl:1
	v_add_f32_dpp v103, v56, v56 row_ror:8 row_mask:0xf bank_mask:0x3
	v_add_f32_dpp v104, v104, v104 row_ror:8 row_mask:0xf bank_mask:0xc
	v_add_f32_dpp v104, v57, v57 row_ror:8 row_mask:0xf bank_mask:0x3
	v_add_f32_dpp v12, v12, v12 row_ror:8 row_mask:0xf bank_mask:0xf bound_ctrl:1
	v_pk_fma_f32 v[6:7], v[24:25], v[12:13], v[48:49] op_sel_hi:[1,0,1] neg_lo:[1,0,0] neg_hi:[1,0,0]
	v_pk_fma_f32 v[8:9], v[26:27], v[12:13], v[50:51] op_sel_hi:[1,0,1] neg_lo:[1,0,0] neg_hi:[1,0,0]
	ds_read_b128 v[110:113], v10 offset:23808
	ds_read_b128 v[106:109], v10 offset:23552
	ds_read_b128 v[118:121], v10 offset:24320
	ds_read_b128 v[114:117], v10 offset:24064
	ds_read_b128 v[66:69], v11 offset:1536
	v_fma_mix_f32 v12, v6, v36, v180 op_sel_hi:[0,1,0]
	v_fma_mix_f32 v12, v7, v36, v12 op_sel:[0,1,0] op_sel_hi:[0,1,0]
	v_fma_mix_f32 v12, v8, v37, v12 op_sel_hi:[0,1,0]
	v_fma_mix_f32 v12, v9, v37, v12 op_sel:[0,1,0] op_sel_hi:[0,1,0]
	v_fma_mix_f32 v126, v6, v22, v180 op_sel_hi:[0,1,0]
	v_fma_mix_f32 v126, v7, v22, v126 op_sel:[0,1,0] op_sel_hi:[0,1,0]
	v_add_f32_dpp v12, v12, v12 row_ror:1 row_mask:0xf bank_mask:0xf bound_ctrl:1
	v_fma_mix_f32 v126, v8, v23, v126 op_sel_hi:[0,1,0]
	v_fma_mix_f32 v126, v9, v23, v126 op_sel:[0,1,0] op_sel_hi:[0,1,0]
	v_add_f32_dpp v12, v12, v12 row_ror:2 row_mask:0xf bank_mask:0xf bound_ctrl:1
	v_pk_fma_f32 v[48:49], v[44:45], v[70:71], v[6:7] op_sel:[0,1,0]
	v_pk_fma_f32 v[50:51], v[46:47], v[70:71], v[8:9] op_sel:[0,1,0]
	v_add_f32_dpp v12, v12, v12 row_ror:4 row_mask:0xf bank_mask:0xf bound_ctrl:1
	v_add_f32_dpp v105, v105, v105 row_ror:8 row_mask:0xf bank_mask:0xc
	v_add_f32_dpp v105, v81, v81 row_ror:8 row_mask:0xf bank_mask:0x3
	v_add_f32_dpp v12, v12, v12 row_ror:8 row_mask:0xf bank_mask:0xf bound_ctrl:1
	v_pk_fma_f32 v[6:7], v[40:41], v[12:13], v[48:49] op_sel_hi:[1,0,1] neg_lo:[1,0,0] neg_hi:[1,0,0]
	v_pk_fma_f32 v[8:9], v[42:43], v[12:13], v[50:51] op_sel_hi:[1,0,1] neg_lo:[1,0,0] neg_hi:[1,0,0]
	s_waitcnt lgkmcnt(1)
	ds_read_b128 v[20:23], v10 offset:24832
	ds_read_b128 v[28:31], v10 offset:25344
	ds_read_b128 v[24:27], v10 offset:25088
	v_fma_mix_f32 v12, v6, v88, v180 op_sel_hi:[0,1,0]
	v_fma_mix_f32 v12, v7, v88, v12 op_sel:[0,1,0] op_sel_hi:[0,1,0]
	v_fma_mix_f32 v12, v8, v89, v12 op_sel_hi:[0,1,0]
	v_fma_mix_f32 v12, v9, v89, v12 op_sel:[0,1,0] op_sel_hi:[0,1,0]
	v_fma_mix_f32 v127, v6, v38, v180 op_sel_hi:[0,1,0]
	v_fma_mix_f32 v127, v7, v38, v127 op_sel:[0,1,0] op_sel_hi:[0,1,0]
	v_add_f32_dpp v12, v12, v12 row_ror:1 row_mask:0xf bank_mask:0xf bound_ctrl:1
	v_fma_mix_f32 v127, v8, v39, v127 op_sel_hi:[0,1,0]
	v_fma_mix_f32 v127, v9, v39, v127 op_sel:[0,1,0] op_sel_hi:[0,1,0]
	v_add_f32_dpp v12, v12, v12 row_ror:2 row_mask:0xf bank_mask:0xf bound_ctrl:1
	v_pk_fma_f32 v[48:49], v[96:97], v[72:73], v[6:7] op_sel_hi:[1,0,1]
	v_pk_fma_f32 v[50:51], v[98:99], v[72:73], v[8:9] op_sel_hi:[1,0,1]
	v_add_f32_dpp v12, v12, v12 row_ror:4 row_mask:0xf bank_mask:0xf bound_ctrl:1
	v_add_f32_dpp v61, v61, v61 row_ror:8 row_mask:0xf bank_mask:0xc
	v_add_f32_dpp v61, v82, v82 row_ror:8 row_mask:0xf bank_mask:0x3
	v_add_f32_dpp v12, v12, v12 row_ror:8 row_mask:0xf bank_mask:0xf bound_ctrl:1
	v_pk_fma_f32 v[6:7], v[92:93], v[12:13], v[48:49] op_sel_hi:[1,0,1] neg_lo:[1,0,0] neg_hi:[1,0,0]
	v_pk_fma_f32 v[8:9], v[94:95], v[12:13], v[50:51] op_sel_hi:[1,0,1] neg_lo:[1,0,0] neg_hi:[1,0,0]
	ds_read_b128 v[36:39], v10 offset:25856
	ds_read_b128 v[44:47], v10 offset:26368
	ds_read_b128 v[40:43], v10 offset:26112
	v_fma_mix_f32 v12, v6, v110, v180 op_sel_hi:[0,1,0]
	v_fma_mix_f32 v12, v7, v110, v12 op_sel:[0,1,0] op_sel_hi:[0,1,0]
	v_fma_mix_f32 v12, v8, v111, v12 op_sel_hi:[0,1,0]
	v_fma_mix_f32 v12, v9, v111, v12 op_sel:[0,1,0] op_sel_hi:[0,1,0]
	v_fma_mix_f32 v128, v6, v90, v180 op_sel_hi:[0,1,0]
	v_fma_mix_f32 v128, v7, v90, v128 op_sel:[0,1,0] op_sel_hi:[0,1,0]
	v_add_f32_dpp v12, v12, v12 row_ror:1 row_mask:0xf bank_mask:0xf bound_ctrl:1
	v_fma_mix_f32 v128, v8, v91, v128 op_sel_hi:[0,1,0]
	v_fma_mix_f32 v128, v9, v91, v128 op_sel:[0,1,0] op_sel_hi:[0,1,0]
	v_add_f32_dpp v12, v12, v12 row_ror:2 row_mask:0xf bank_mask:0xf bound_ctrl:1
	v_pk_fma_f32 v[48:49], v[118:119], v[72:73], v[6:7] op_sel:[0,1,0]
	v_pk_fma_f32 v[50:51], v[120:121], v[72:73], v[8:9] op_sel:[0,1,0]
	v_add_f32_dpp v12, v12, v12 row_ror:4 row_mask:0xf bank_mask:0xf bound_ctrl:1
	v_add_f32_dpp v103, v103, v103 row_ror:4 row_mask:0xf bank_mask:0xa
	v_add_f32_dpp v103, v83, v83 row_ror:12 row_mask:0xf bank_mask:0x5
	v_add_f32_dpp v104, v104, v104 row_ror:4 row_mask:0xf bank_mask:0xa
	v_add_f32_dpp v12, v12, v12 row_ror:8 row_mask:0xf bank_mask:0xf bound_ctrl:1
	v_pk_fma_f32 v[6:7], v[114:115], v[12:13], v[48:49] op_sel_hi:[1,0,1] neg_lo:[1,0,0] neg_hi:[1,0,0]
	v_pk_fma_f32 v[8:9], v[116:117], v[12:13], v[50:51] op_sel_hi:[1,0,1] neg_lo:[1,0,0] neg_hi:[1,0,0]
	v_pk_mul_f32 v[6:7], v[6:7], v[106:107]
	v_pk_mul_f32 v[8:9], v[8:9], v[108:109]
	s_waitcnt lgkmcnt(0)
	ds_read_b128 v[88:91], v10 offset:26880
	ds_read_b128 v[96:99], v10 offset:27392
	ds_read_b128 v[92:95], v10 offset:27136
	v_fma_mix_f32 v12, v6, v20, v180 op_sel_hi:[0,1,0]
	v_fma_mix_f32 v12, v7, v20, v12 op_sel:[0,1,0] op_sel_hi:[0,1,0]
	v_fma_mix_f32 v12, v8, v21, v12 op_sel_hi:[0,1,0]
	v_fma_mix_f32 v12, v9, v21, v12 op_sel:[0,1,0] op_sel_hi:[0,1,0]
	v_fma_mix_f32 v129, v6, v112, v180 op_sel_hi:[0,1,0]
	v_fma_mix_f32 v129, v7, v112, v129 op_sel:[0,1,0] op_sel_hi:[0,1,0]
	v_add_f32_dpp v12, v12, v12 row_ror:1 row_mask:0xf bank_mask:0xf bound_ctrl:1
	v_fma_mix_f32 v129, v8, v113, v129 op_sel_hi:[0,1,0]
	v_fma_mix_f32 v129, v9, v113, v129 op_sel:[0,1,0] op_sel_hi:[0,1,0]
	v_add_f32_dpp v12, v12, v12 row_ror:2 row_mask:0xf bank_mask:0xf bound_ctrl:1
	v_pk_fma_f32 v[48:49], v[28:29], v[66:67], v[6:7] op_sel_hi:[1,0,1]
	v_pk_fma_f32 v[50:51], v[30:31], v[66:67], v[8:9] op_sel_hi:[1,0,1]
	v_add_f32_dpp v12, v12, v12 row_ror:4 row_mask:0xf bank_mask:0xf bound_ctrl:1
	v_add_f32_dpp v104, v100, v100 row_ror:12 row_mask:0xf bank_mask:0x5
	v_add_f32_dpp v105, v105, v105 row_ror:4 row_mask:0xf bank_mask:0xa
	v_add_f32_dpp v105, v101, v101 row_ror:12 row_mask:0xf bank_mask:0x5
	v_add_f32_dpp v12, v12, v12 row_ror:8 row_mask:0xf bank_mask:0xf bound_ctrl:1
	v_pk_fma_f32 v[6:7], v[24:25], v[12:13], v[48:49] op_sel_hi:[1,0,1] neg_lo:[1,0,0] neg_hi:[1,0,0]
	v_pk_fma_f32 v[8:9], v[26:27], v[12:13], v[50:51] op_sel_hi:[1,0,1] neg_lo:[1,0,0] neg_hi:[1,0,0]
	ds_read_b128 v[110:113], v10 offset:27904
	ds_read_b128 v[106:109], v10 offset:27648
	ds_read_b128 v[118:121], v10 offset:28416
	ds_read_b128 v[114:117], v10 offset:28160
	ds_read_b128 v[70:73], v11 offset:1792
	v_fma_mix_f32 v12, v6, v36, v180 op_sel_hi:[0,1,0]
	v_fma_mix_f32 v12, v7, v36, v12 op_sel:[0,1,0] op_sel_hi:[0,1,0]
	v_fma_mix_f32 v12, v8, v37, v12 op_sel_hi:[0,1,0]
	v_fma_mix_f32 v12, v9, v37, v12 op_sel:[0,1,0] op_sel_hi:[0,1,0]
	v_fma_mix_f32 v130, v6, v22, v180 op_sel_hi:[0,1,0]
	v_fma_mix_f32 v130, v7, v22, v130 op_sel:[0,1,0] op_sel_hi:[0,1,0]
	v_add_f32_dpp v12, v12, v12 row_ror:1 row_mask:0xf bank_mask:0xf bound_ctrl:1
	v_fma_mix_f32 v130, v8, v23, v130 op_sel_hi:[0,1,0]
	v_fma_mix_f32 v130, v9, v23, v130 op_sel:[0,1,0] op_sel_hi:[0,1,0]
	v_add_f32_dpp v12, v12, v12 row_ror:2 row_mask:0xf bank_mask:0xf bound_ctrl:1
	v_pk_fma_f32 v[48:49], v[44:45], v[66:67], v[6:7] op_sel:[0,1,0]
	v_pk_fma_f32 v[50:51], v[46:47], v[66:67], v[8:9] op_sel:[0,1,0]
	v_add_f32_dpp v12, v12, v12 row_ror:4 row_mask:0xf bank_mask:0xf bound_ctrl:1
	v_add_f32_dpp v61, v61, v61 row_ror:4 row_mask:0xf bank_mask:0xa
	v_add_f32_dpp v61, v102, v102 row_ror:12 row_mask:0xf bank_mask:0x5
	v_add_f32_dpp v12, v12, v12 row_ror:8 row_mask:0xf bank_mask:0xf bound_ctrl:1
	v_pk_fma_f32 v[6:7], v[40:41], v[12:13], v[48:49] op_sel_hi:[1,0,1] neg_lo:[1,0,0] neg_hi:[1,0,0]
	v_pk_fma_f32 v[8:9], v[42:43], v[12:13], v[50:51] op_sel_hi:[1,0,1] neg_lo:[1,0,0] neg_hi:[1,0,0]
	s_waitcnt lgkmcnt(1)
	ds_read_b128 v[20:23], v10 offset:28928
	ds_read_b128 v[28:31], v10 offset:29440
	ds_read_b128 v[24:27], v10 offset:29184
	v_fma_mix_f32 v12, v6, v88, v180 op_sel_hi:[0,1,0]
	v_fma_mix_f32 v12, v7, v88, v12 op_sel:[0,1,0] op_sel_hi:[0,1,0]
	v_fma_mix_f32 v12, v8, v89, v12 op_sel_hi:[0,1,0]
	v_fma_mix_f32 v12, v9, v89, v12 op_sel:[0,1,0] op_sel_hi:[0,1,0]
	v_fma_mix_f32 v131, v6, v38, v180 op_sel_hi:[0,1,0]
	v_fma_mix_f32 v131, v7, v38, v131 op_sel:[0,1,0] op_sel_hi:[0,1,0]
	v_add_f32_dpp v12, v12, v12 row_ror:1 row_mask:0xf bank_mask:0xf bound_ctrl:1
	v_fma_mix_f32 v131, v8, v39, v131 op_sel_hi:[0,1,0]
	v_fma_mix_f32 v131, v9, v39, v131 op_sel:[0,1,0] op_sel_hi:[0,1,0]
	v_add_f32_dpp v12, v12, v12 row_ror:2 row_mask:0xf bank_mask:0xf bound_ctrl:1
	v_pk_fma_f32 v[48:49], v[96:97], v[68:69], v[6:7] op_sel_hi:[1,0,1]
	v_pk_fma_f32 v[50:51], v[98:99], v[68:69], v[8:9] op_sel_hi:[1,0,1]
	v_add_f32_dpp v12, v12, v12 row_ror:4 row_mask:0xf bank_mask:0xf bound_ctrl:1
	v_cndmask_b32_e64 v62, v105, v103, s[38:39]
	v_cndmask_b32_e64 v63, v103, v105, s[38:39]
	v_add_f32_dpp v12, v12, v12 row_ror:8 row_mask:0xf bank_mask:0xf bound_ctrl:1
	v_pk_fma_f32 v[6:7], v[92:93], v[12:13], v[48:49] op_sel_hi:[1,0,1] neg_lo:[1,0,0] neg_hi:[1,0,0]
	v_pk_fma_f32 v[8:9], v[94:95], v[12:13], v[50:51] op_sel_hi:[1,0,1] neg_lo:[1,0,0] neg_hi:[1,0,0]
	ds_read_b128 v[36:39], v10 offset:29952
	ds_read_b128 v[44:47], v10 offset:30464
	ds_read_b128 v[40:43], v10 offset:30208
	v_fma_mix_f32 v12, v6, v110, v180 op_sel_hi:[0,1,0]
	v_fma_mix_f32 v12, v7, v110, v12 op_sel:[0,1,0] op_sel_hi:[0,1,0]
	v_fma_mix_f32 v12, v8, v111, v12 op_sel_hi:[0,1,0]
	v_fma_mix_f32 v12, v9, v111, v12 op_sel:[0,1,0] op_sel_hi:[0,1,0]
	v_fma_mix_f32 v132, v6, v90, v180 op_sel_hi:[0,1,0]
	v_fma_mix_f32 v132, v7, v90, v132 op_sel:[0,1,0] op_sel_hi:[0,1,0]
	v_add_f32_dpp v12, v12, v12 row_ror:1 row_mask:0xf bank_mask:0xf bound_ctrl:1
	v_fma_mix_f32 v132, v8, v91, v132 op_sel_hi:[0,1,0]
	v_fma_mix_f32 v132, v9, v91, v132 op_sel:[0,1,0] op_sel_hi:[0,1,0]
	v_add_f32_dpp v12, v12, v12 row_ror:2 row_mask:0xf bank_mask:0xf bound_ctrl:1
	v_pk_fma_f32 v[48:49], v[118:119], v[68:69], v[6:7] op_sel:[0,1,0]
	v_pk_fma_f32 v[50:51], v[120:121], v[68:69], v[8:9] op_sel:[0,1,0]
	v_add_f32_dpp v12, v12, v12 row_ror:4 row_mask:0xf bank_mask:0xf bound_ctrl:1
	v_cndmask_b32_e64 v64, v61, v104, s[38:39]
	v_cndmask_b32_e64 v65, v104, v61, s[38:39]
	v_add_f32_dpp v12, v12, v12 row_ror:8 row_mask:0xf bank_mask:0xf bound_ctrl:1
	v_pk_fma_f32 v[6:7], v[114:115], v[12:13], v[48:49] op_sel_hi:[1,0,1] neg_lo:[1,0,0] neg_hi:[1,0,0]
	v_pk_fma_f32 v[8:9], v[116:117], v[12:13], v[50:51] op_sel_hi:[1,0,1] neg_lo:[1,0,0] neg_hi:[1,0,0]
	v_pk_mul_f32 v[6:7], v[6:7], v[106:107]
	v_pk_mul_f32 v[8:9], v[8:9], v[108:109]
	s_waitcnt lgkmcnt(0)
	ds_read_b128 v[88:91], v10 offset:30976
	ds_read_b128 v[96:99], v10 offset:31488
	ds_read_b128 v[92:95], v10 offset:31232
	v_fma_mix_f32 v12, v6, v20, v180 op_sel_hi:[0,1,0]
	v_fma_mix_f32 v12, v7, v20, v12 op_sel:[0,1,0] op_sel_hi:[0,1,0]
	v_fma_mix_f32 v12, v8, v21, v12 op_sel_hi:[0,1,0]
	v_fma_mix_f32 v12, v9, v21, v12 op_sel:[0,1,0] op_sel_hi:[0,1,0]
	v_fma_mix_f32 v133, v6, v112, v180 op_sel_hi:[0,1,0]
	v_fma_mix_f32 v133, v7, v112, v133 op_sel:[0,1,0] op_sel_hi:[0,1,0]
	v_add_f32_dpp v12, v12, v12 row_ror:1 row_mask:0xf bank_mask:0xf bound_ctrl:1
	v_fma_mix_f32 v133, v8, v113, v133 op_sel_hi:[0,1,0]
	v_fma_mix_f32 v133, v9, v113, v133 op_sel:[0,1,0] op_sel_hi:[0,1,0]
	v_add_f32_dpp v12, v12, v12 row_ror:2 row_mask:0xf bank_mask:0xf bound_ctrl:1
	v_pk_fma_f32 v[48:49], v[28:29], v[70:71], v[6:7] op_sel_hi:[1,0,1]
	v_pk_fma_f32 v[50:51], v[30:31], v[70:71], v[8:9] op_sel_hi:[1,0,1]
	v_add_f32_dpp v12, v12, v12 row_ror:4 row_mask:0xf bank_mask:0xf bound_ctrl:1
	v_add_f32_dpp v62, v63, v62 quad_perm:[2,3,0,1] row_mask:0xf bank_mask:0xf bound_ctrl:1
	v_add_f32_dpp v63, v65, v64 quad_perm:[2,3,0,1] row_mask:0xf bank_mask:0xf bound_ctrl:1
	v_add_f32_dpp v12, v12, v12 row_ror:8 row_mask:0xf bank_mask:0xf bound_ctrl:1
	v_pk_fma_f32 v[6:7], v[24:25], v[12:13], v[48:49] op_sel_hi:[1,0,1] neg_lo:[1,0,0] neg_hi:[1,0,0]
	v_pk_fma_f32 v[8:9], v[26:27], v[12:13], v[50:51] op_sel_hi:[1,0,1] neg_lo:[1,0,0] neg_hi:[1,0,0]
	ds_read_b128 v[110:113], v10 offset:32000
	ds_read_b128 v[106:109], v10 offset:31744
	ds_read_b128 v[118:121], v10 offset:32512
	ds_read_b128 v[114:117], v10 offset:32256
	ds_read_b128 v[66:69], v11 offset:2048
	v_fma_mix_f32 v12, v6, v36, v180 op_sel_hi:[0,1,0]
	v_fma_mix_f32 v12, v7, v36, v12 op_sel:[0,1,0] op_sel_hi:[0,1,0]
	v_fma_mix_f32 v12, v8, v37, v12 op_sel_hi:[0,1,0]
	v_fma_mix_f32 v12, v9, v37, v12 op_sel:[0,1,0] op_sel_hi:[0,1,0]
	v_fma_mix_f32 v134, v6, v22, v180 op_sel_hi:[0,1,0]
	v_fma_mix_f32 v134, v7, v22, v134 op_sel:[0,1,0] op_sel_hi:[0,1,0]
	v_add_f32_dpp v12, v12, v12 row_ror:1 row_mask:0xf bank_mask:0xf bound_ctrl:1
	v_fma_mix_f32 v134, v8, v23, v134 op_sel_hi:[0,1,0]
	v_fma_mix_f32 v134, v9, v23, v134 op_sel:[0,1,0] op_sel_hi:[0,1,0]
	v_add_f32_dpp v12, v12, v12 row_ror:2 row_mask:0xf bank_mask:0xf bound_ctrl:1
	v_pk_fma_f32 v[48:49], v[44:45], v[70:71], v[6:7] op_sel:[0,1,0]
	v_pk_fma_f32 v[50:51], v[46:47], v[70:71], v[8:9] op_sel:[0,1,0]
	v_add_f32_dpp v12, v12, v12 row_ror:4 row_mask:0xf bank_mask:0xf bound_ctrl:1
	v_cndmask_b32_e64 v65, v63, v62, s[40:41]
	v_cndmask_b32_e64 v62, v62, v63, s[40:41]
	v_add_f32_dpp v12, v12, v12 row_ror:8 row_mask:0xf bank_mask:0xf bound_ctrl:1
	v_pk_fma_f32 v[6:7], v[40:41], v[12:13], v[48:49] op_sel_hi:[1,0,1] neg_lo:[1,0,0] neg_hi:[1,0,0]
	v_pk_fma_f32 v[8:9], v[42:43], v[12:13], v[50:51] op_sel_hi:[1,0,1] neg_lo:[1,0,0] neg_hi:[1,0,0]
	s_waitcnt lgkmcnt(1)
	ds_read_b128 v[20:23], v10 offset:33024
	ds_read_b128 v[28:31], v10 offset:33536
	ds_read_b128 v[24:27], v10 offset:33280
	v_fma_mix_f32 v12, v6, v88, v180 op_sel_hi:[0,1,0]
	v_fma_mix_f32 v12, v7, v88, v12 op_sel:[0,1,0] op_sel_hi:[0,1,0]
	v_fma_mix_f32 v12, v8, v89, v12 op_sel_hi:[0,1,0]
	v_fma_mix_f32 v12, v9, v89, v12 op_sel:[0,1,0] op_sel_hi:[0,1,0]
	v_fma_mix_f32 v135, v6, v38, v180 op_sel_hi:[0,1,0]
	v_fma_mix_f32 v135, v7, v38, v135 op_sel:[0,1,0] op_sel_hi:[0,1,0]
	v_add_f32_dpp v12, v12, v12 row_ror:1 row_mask:0xf bank_mask:0xf bound_ctrl:1
	v_fma_mix_f32 v135, v8, v39, v135 op_sel_hi:[0,1,0]
	v_fma_mix_f32 v135, v9, v39, v135 op_sel:[0,1,0] op_sel_hi:[0,1,0]
	v_add_f32_dpp v12, v12, v12 row_ror:2 row_mask:0xf bank_mask:0xf bound_ctrl:1
	v_pk_fma_f32 v[48:49], v[96:97], v[72:73], v[6:7] op_sel_hi:[1,0,1]
	v_pk_fma_f32 v[50:51], v[98:99], v[72:73], v[8:9] op_sel_hi:[1,0,1]
	v_add_f32_dpp v12, v12, v12 row_ror:4 row_mask:0xf bank_mask:0xf bound_ctrl:1
	v_add_f32_dpp v62, v62, v65 quad_perm:[1,0,3,2] row_mask:0xf bank_mask:0xf bound_ctrl:1
	v_cvt_pk_bf16_f32 v62, v62, v62
	v_add_f32_dpp v12, v12, v12 row_ror:8 row_mask:0xf bank_mask:0xf bound_ctrl:1
	v_pk_fma_f32 v[6:7], v[92:93], v[12:13], v[48:49] op_sel_hi:[1,0,1] neg_lo:[1,0,0] neg_hi:[1,0,0]
	v_pk_fma_f32 v[8:9], v[94:95], v[12:13], v[50:51] op_sel_hi:[1,0,1] neg_lo:[1,0,0] neg_hi:[1,0,0]
	ds_read_b128 v[36:39], v10 offset:34048
	ds_read_b128 v[44:47], v10 offset:34560
	ds_read_b128 v[40:43], v10 offset:34304
	v_fma_mix_f32 v12, v6, v110, v180 op_sel_hi:[0,1,0]
	v_fma_mix_f32 v12, v7, v110, v12 op_sel:[0,1,0] op_sel_hi:[0,1,0]
	v_fma_mix_f32 v12, v8, v111, v12 op_sel_hi:[0,1,0]
	v_fma_mix_f32 v12, v9, v111, v12 op_sel:[0,1,0] op_sel_hi:[0,1,0]
	v_fma_mix_f32 v136, v6, v90, v180 op_sel_hi:[0,1,0]
	v_fma_mix_f32 v136, v7, v90, v136 op_sel:[0,1,0] op_sel_hi:[0,1,0]
	v_add_f32_dpp v12, v12, v12 row_ror:1 row_mask:0xf bank_mask:0xf bound_ctrl:1
	v_fma_mix_f32 v136, v8, v91, v136 op_sel_hi:[0,1,0]
	v_fma_mix_f32 v136, v9, v91, v136 op_sel:[0,1,0] op_sel_hi:[0,1,0]
	v_add_f32_dpp v12, v12, v12 row_ror:2 row_mask:0xf bank_mask:0xf bound_ctrl:1
	v_pk_fma_f32 v[48:49], v[118:119], v[72:73], v[6:7] op_sel:[0,1,0]
	v_pk_fma_f32 v[50:51], v[120:121], v[72:73], v[8:9] op_sel:[0,1,0]
	v_add_f32_dpp v12, v12, v12 row_ror:4 row_mask:0xf bank_mask:0xf bound_ctrl:1
	global_store_short v[2:3], v62, off
	v_lshl_add_u64 v[2:3], v[2:3], 0, s[84:85]
	v_add_f32_dpp v12, v12, v12 row_ror:8 row_mask:0xf bank_mask:0xf bound_ctrl:1
	v_pk_fma_f32 v[6:7], v[114:115], v[12:13], v[48:49] op_sel_hi:[1,0,1] neg_lo:[1,0,0] neg_hi:[1,0,0]
	v_pk_fma_f32 v[8:9], v[116:117], v[12:13], v[50:51] op_sel_hi:[1,0,1] neg_lo:[1,0,0] neg_hi:[1,0,0]
	v_pk_mul_f32 v[6:7], v[6:7], v[106:107]
	v_pk_mul_f32 v[8:9], v[8:9], v[108:109]
	s_waitcnt lgkmcnt(0)
	ds_read_b128 v[88:91], v10 offset:35072
	ds_read_b128 v[96:99], v10 offset:35584
	ds_read_b128 v[92:95], v10 offset:35328
	v_fma_mix_f32 v12, v6, v20, v180 op_sel_hi:[0,1,0]
	v_fma_mix_f32 v12, v7, v20, v12 op_sel:[0,1,0] op_sel_hi:[0,1,0]
	v_fma_mix_f32 v12, v8, v21, v12 op_sel_hi:[0,1,0]
	v_fma_mix_f32 v12, v9, v21, v12 op_sel:[0,1,0] op_sel_hi:[0,1,0]
	v_fma_mix_f32 v137, v6, v112, v180 op_sel_hi:[0,1,0]
	v_fma_mix_f32 v137, v7, v112, v137 op_sel:[0,1,0] op_sel_hi:[0,1,0]
	v_add_f32_dpp v12, v12, v12 row_ror:1 row_mask:0xf bank_mask:0xf bound_ctrl:1
	v_fma_mix_f32 v137, v8, v113, v137 op_sel_hi:[0,1,0]
	v_fma_mix_f32 v137, v9, v113, v137 op_sel:[0,1,0] op_sel_hi:[0,1,0]
	v_add_f32_dpp v12, v12, v12 row_ror:2 row_mask:0xf bank_mask:0xf bound_ctrl:1
	v_pk_fma_f32 v[48:49], v[28:29], v[66:67], v[6:7] op_sel_hi:[1,0,1]
	v_pk_fma_f32 v[50:51], v[30:31], v[66:67], v[8:9] op_sel_hi:[1,0,1]
	v_add_f32_dpp v12, v12, v12 row_ror:4 row_mask:0xf bank_mask:0xf bound_ctrl:1
	s_nop 1
	v_add_f32_dpp v12, v12, v12 row_ror:8 row_mask:0xf bank_mask:0xf bound_ctrl:1
	v_pk_fma_f32 v[6:7], v[24:25], v[12:13], v[48:49] op_sel_hi:[1,0,1] neg_lo:[1,0,0] neg_hi:[1,0,0]
	v_pk_fma_f32 v[8:9], v[26:27], v[12:13], v[50:51] op_sel_hi:[1,0,1] neg_lo:[1,0,0] neg_hi:[1,0,0]
	ds_read_b128 v[110:113], v10 offset:36096
	ds_read_b128 v[106:109], v10 offset:35840
	ds_read_b128 v[118:121], v10 offset:36608
	ds_read_b128 v[114:117], v10 offset:36352
	ds_read_b128 v[70:73], v11 offset:2304
	v_fma_mix_f32 v12, v6, v36, v180 op_sel_hi:[0,1,0]
	v_fma_mix_f32 v12, v7, v36, v12 op_sel:[0,1,0] op_sel_hi:[0,1,0]
	v_fma_mix_f32 v12, v8, v37, v12 op_sel_hi:[0,1,0]
	v_fma_mix_f32 v12, v9, v37, v12 op_sel:[0,1,0] op_sel_hi:[0,1,0]
	v_fma_mix_f32 v52, v6, v22, v180 op_sel_hi:[0,1,0]
	v_fma_mix_f32 v52, v7, v22, v52 op_sel:[0,1,0] op_sel_hi:[0,1,0]
	v_add_f32_dpp v12, v12, v12 row_ror:1 row_mask:0xf bank_mask:0xf bound_ctrl:1
	v_fma_mix_f32 v52, v8, v23, v52 op_sel_hi:[0,1,0]
	v_fma_mix_f32 v52, v9, v23, v52 op_sel:[0,1,0] op_sel_hi:[0,1,0]
	v_add_f32_dpp v12, v12, v12 row_ror:2 row_mask:0xf bank_mask:0xf bound_ctrl:1
	v_pk_fma_f32 v[48:49], v[44:45], v[66:67], v[6:7] op_sel:[0,1,0]
	v_pk_fma_f32 v[50:51], v[46:47], v[66:67], v[8:9] op_sel:[0,1,0]
	v_add_f32_dpp v12, v12, v12 row_ror:4 row_mask:0xf bank_mask:0xf bound_ctrl:1
	v_add_f32_dpp v130, v130, v130 row_ror:8 row_mask:0xf bank_mask:0xc
	v_add_f32_dpp v130, v122, v122 row_ror:8 row_mask:0xf bank_mask:0x3
	v_add_f32_dpp v131, v131, v131 row_ror:8 row_mask:0xf bank_mask:0xc
	v_add_f32_dpp v12, v12, v12 row_ror:8 row_mask:0xf bank_mask:0xf bound_ctrl:1
	v_pk_fma_f32 v[6:7], v[40:41], v[12:13], v[48:49] op_sel_hi:[1,0,1] neg_lo:[1,0,0] neg_hi:[1,0,0]
	v_pk_fma_f32 v[8:9], v[42:43], v[12:13], v[50:51] op_sel_hi:[1,0,1] neg_lo:[1,0,0] neg_hi:[1,0,0]
	s_waitcnt lgkmcnt(1)
	ds_read_b128 v[20:23], v10 offset:37120
	ds_read_b128 v[28:31], v10 offset:37632
	ds_read_b128 v[24:27], v10 offset:37376
	v_fma_mix_f32 v12, v6, v88, v180 op_sel_hi:[0,1,0]
	v_fma_mix_f32 v12, v7, v88, v12 op_sel:[0,1,0] op_sel_hi:[0,1,0]
	v_fma_mix_f32 v12, v8, v89, v12 op_sel_hi:[0,1,0]
	v_fma_mix_f32 v12, v9, v89, v12 op_sel:[0,1,0] op_sel_hi:[0,1,0]
	v_fma_mix_f32 v53, v6, v38, v180 op_sel_hi:[0,1,0]
	v_fma_mix_f32 v53, v7, v38, v53 op_sel:[0,1,0] op_sel_hi:[0,1,0]
	v_add_f32_dpp v12, v12, v12 row_ror:1 row_mask:0xf bank_mask:0xf bound_ctrl:1
	v_fma_mix_f32 v53, v8, v39, v53 op_sel_hi:[0,1,0]
	v_fma_mix_f32 v53, v9, v39, v53 op_sel:[0,1,0] op_sel_hi:[0,1,0]
	v_add_f32_dpp v12, v12, v12 row_ror:2 row_mask:0xf bank_mask:0xf bound_ctrl:1
	v_pk_fma_f32 v[48:49], v[96:97], v[68:69], v[6:7] op_sel_hi:[1,0,1]
	v_pk_fma_f32 v[50:51], v[98:99], v[68:69], v[8:9] op_sel_hi:[1,0,1]
	v_add_f32_dpp v12, v12, v12 row_ror:4 row_mask:0xf bank_mask:0xf bound_ctrl:1
	v_add_f32_dpp v131, v123, v123 row_ror:8 row_mask:0xf bank_mask:0x3
	v_add_f32_dpp v132, v132, v132 row_ror:8 row_mask:0xf bank_mask:0xc
	v_add_f32_dpp v132, v124, v124 row_ror:8 row_mask:0xf bank_mask:0x3
	v_add_f32_dpp v12, v12, v12 row_ror:8 row_mask:0xf bank_mask:0xf bound_ctrl:1
	v_pk_fma_f32 v[6:7], v[92:93], v[12:13], v[48:49] op_sel_hi:[1,0,1] neg_lo:[1,0,0] neg_hi:[1,0,0]
	v_pk_fma_f32 v[8:9], v[94:95], v[12:13], v[50:51] op_sel_hi:[1,0,1] neg_lo:[1,0,0] neg_hi:[1,0,0]
	ds_read_b128 v[36:39], v10 offset:38144
	ds_read_b128 v[44:47], v10 offset:38656
	ds_read_b128 v[40:43], v10 offset:38400
	v_fma_mix_f32 v12, v6, v110, v180 op_sel_hi:[0,1,0]
	v_fma_mix_f32 v12, v7, v110, v12 op_sel:[0,1,0] op_sel_hi:[0,1,0]
	v_fma_mix_f32 v12, v8, v111, v12 op_sel_hi:[0,1,0]
	v_fma_mix_f32 v12, v9, v111, v12 op_sel:[0,1,0] op_sel_hi:[0,1,0]
	v_fma_mix_f32 v54, v6, v90, v180 op_sel_hi:[0,1,0]
	v_fma_mix_f32 v54, v7, v90, v54 op_sel:[0,1,0] op_sel_hi:[0,1,0]
	v_add_f32_dpp v12, v12, v12 row_ror:1 row_mask:0xf bank_mask:0xf bound_ctrl:1
	v_fma_mix_f32 v54, v8, v91, v54 op_sel_hi:[0,1,0]
	v_fma_mix_f32 v54, v9, v91, v54 op_sel:[0,1,0] op_sel_hi:[0,1,0]
	v_add_f32_dpp v12, v12, v12 row_ror:2 row_mask:0xf bank_mask:0xf bound_ctrl:1
	v_pk_fma_f32 v[48:49], v[118:119], v[68:69], v[6:7] op_sel:[0,1,0]
	v_pk_fma_f32 v[50:51], v[120:121], v[68:69], v[8:9] op_sel:[0,1,0]
	v_add_f32_dpp v12, v12, v12 row_ror:4 row_mask:0xf bank_mask:0xf bound_ctrl:1
	v_add_f32_dpp v133, v133, v133 row_ror:8 row_mask:0xf bank_mask:0xc
	v_add_f32_dpp v133, v125, v125 row_ror:8 row_mask:0xf bank_mask:0x3
	v_add_f32_dpp v134, v134, v134 row_ror:8 row_mask:0xf bank_mask:0xc
	v_add_f32_dpp v12, v12, v12 row_ror:8 row_mask:0xf bank_mask:0xf bound_ctrl:1
	v_pk_fma_f32 v[6:7], v[114:115], v[12:13], v[48:49] op_sel_hi:[1,0,1] neg_lo:[1,0,0] neg_hi:[1,0,0]
	v_pk_fma_f32 v[8:9], v[116:117], v[12:13], v[50:51] op_sel_hi:[1,0,1] neg_lo:[1,0,0] neg_hi:[1,0,0]
	v_pk_mul_f32 v[6:7], v[6:7], v[106:107]
	v_pk_mul_f32 v[8:9], v[8:9], v[108:109]
	s_waitcnt lgkmcnt(0)
	ds_read_b128 v[88:91], v10 offset:39168
	ds_read_b128 v[96:99], v10 offset:39680
	ds_read_b128 v[92:95], v10 offset:39424
	v_fma_mix_f32 v12, v6, v20, v180 op_sel_hi:[0,1,0]
	v_fma_mix_f32 v12, v7, v20, v12 op_sel:[0,1,0] op_sel_hi:[0,1,0]
	v_fma_mix_f32 v12, v8, v21, v12 op_sel_hi:[0,1,0]
	v_fma_mix_f32 v12, v9, v21, v12 op_sel:[0,1,0] op_sel_hi:[0,1,0]
	v_fma_mix_f32 v55, v6, v112, v180 op_sel_hi:[0,1,0]
	v_fma_mix_f32 v55, v7, v112, v55 op_sel:[0,1,0] op_sel_hi:[0,1,0]
	v_add_f32_dpp v12, v12, v12 row_ror:1 row_mask:0xf bank_mask:0xf bound_ctrl:1
	v_fma_mix_f32 v55, v8, v113, v55 op_sel_hi:[0,1,0]
	v_fma_mix_f32 v55, v9, v113, v55 op_sel:[0,1,0] op_sel_hi:[0,1,0]
	v_add_f32_dpp v12, v12, v12 row_ror:2 row_mask:0xf bank_mask:0xf bound_ctrl:1
	v_pk_fma_f32 v[48:49], v[28:29], v[70:71], v[6:7] op_sel_hi:[1,0,1]
	v_pk_fma_f32 v[50:51], v[30:31], v[70:71], v[8:9] op_sel_hi:[1,0,1]
	v_add_f32_dpp v12, v12, v12 row_ror:4 row_mask:0xf bank_mask:0xf bound_ctrl:1
	v_add_f32_dpp v134, v126, v126 row_ror:8 row_mask:0xf bank_mask:0x3
	v_add_f32_dpp v135, v135, v135 row_ror:8 row_mask:0xf bank_mask:0xc
	v_add_f32_dpp v135, v127, v127 row_ror:8 row_mask:0xf bank_mask:0x3
	v_add_f32_dpp v12, v12, v12 row_ror:8 row_mask:0xf bank_mask:0xf bound_ctrl:1
	v_pk_fma_f32 v[6:7], v[24:25], v[12:13], v[48:49] op_sel_hi:[1,0,1] neg_lo:[1,0,0] neg_hi:[1,0,0]
	v_pk_fma_f32 v[8:9], v[26:27], v[12:13], v[50:51] op_sel_hi:[1,0,1] neg_lo:[1,0,0] neg_hi:[1,0,0]
	ds_read_b128 v[110:113], v10 offset:40192
	ds_read_b128 v[106:109], v10 offset:39936
	ds_read_b128 v[118:121], v10 offset:40704
	ds_read_b128 v[114:117], v10 offset:40448
	ds_read_b128 v[66:69], v11 offset:2560
	v_fma_mix_f32 v12, v6, v36, v180 op_sel_hi:[0,1,0]
	v_fma_mix_f32 v12, v7, v36, v12 op_sel:[0,1,0] op_sel_hi:[0,1,0]
	v_fma_mix_f32 v12, v8, v37, v12 op_sel_hi:[0,1,0]
	v_fma_mix_f32 v12, v9, v37, v12 op_sel:[0,1,0] op_sel_hi:[0,1,0]
	v_fma_mix_f32 v56, v6, v22, v180 op_sel_hi:[0,1,0]
	v_fma_mix_f32 v56, v7, v22, v56 op_sel:[0,1,0] op_sel_hi:[0,1,0]
	v_add_f32_dpp v12, v12, v12 row_ror:1 row_mask:0xf bank_mask:0xf bound_ctrl:1
	v_fma_mix_f32 v56, v8, v23, v56 op_sel_hi:[0,1,0]
	v_fma_mix_f32 v56, v9, v23, v56 op_sel:[0,1,0] op_sel_hi:[0,1,0]
	v_add_f32_dpp v12, v12, v12 row_ror:2 row_mask:0xf bank_mask:0xf bound_ctrl:1
	v_pk_fma_f32 v[48:49], v[44:45], v[70:71], v[6:7] op_sel:[0,1,0]
	v_pk_fma_f32 v[50:51], v[46:47], v[70:71], v[8:9] op_sel:[0,1,0]
	v_add_f32_dpp v12, v12, v12 row_ror:4 row_mask:0xf bank_mask:0xf bound_ctrl:1
	v_add_f32_dpp v136, v136, v136 row_ror:8 row_mask:0xf bank_mask:0xc
	v_add_f32_dpp v136, v128, v128 row_ror:8 row_mask:0xf bank_mask:0x3
	v_add_f32_dpp v12, v12, v12 row_ror:8 row_mask:0xf bank_mask:0xf bound_ctrl:1
	v_pk_fma_f32 v[6:7], v[40:41], v[12:13], v[48:49] op_sel_hi:[1,0,1] neg_lo:[1,0,0] neg_hi:[1,0,0]
	v_pk_fma_f32 v[8:9], v[42:43], v[12:13], v[50:51] op_sel_hi:[1,0,1] neg_lo:[1,0,0] neg_hi:[1,0,0]
	s_waitcnt lgkmcnt(1)
	ds_read_b128 v[20:23], v10 offset:41216
	ds_read_b128 v[28:31], v10 offset:41728
	ds_read_b128 v[24:27], v10 offset:41472
	v_fma_mix_f32 v12, v6, v88, v180 op_sel_hi:[0,1,0]
	v_fma_mix_f32 v12, v7, v88, v12 op_sel:[0,1,0] op_sel_hi:[0,1,0]
	v_fma_mix_f32 v12, v8, v89, v12 op_sel_hi:[0,1,0]
	v_fma_mix_f32 v12, v9, v89, v12 op_sel:[0,1,0] op_sel_hi:[0,1,0]
	v_fma_mix_f32 v57, v6, v38, v180 op_sel_hi:[0,1,0]
	v_fma_mix_f32 v57, v7, v38, v57 op_sel:[0,1,0] op_sel_hi:[0,1,0]
	v_add_f32_dpp v12, v12, v12 row_ror:1 row_mask:0xf bank_mask:0xf bound_ctrl:1
	v_fma_mix_f32 v57, v8, v39, v57 op_sel_hi:[0,1,0]
	v_fma_mix_f32 v57, v9, v39, v57 op_sel:[0,1,0] op_sel_hi:[0,1,0]
	v_add_f32_dpp v12, v12, v12 row_ror:2 row_mask:0xf bank_mask:0xf bound_ctrl:1
	v_pk_fma_f32 v[48:49], v[96:97], v[72:73], v[6:7] op_sel_hi:[1,0,1]
	v_pk_fma_f32 v[50:51], v[98:99], v[72:73], v[8:9] op_sel_hi:[1,0,1]
	v_add_f32_dpp v12, v12, v12 row_ror:4 row_mask:0xf bank_mask:0xf bound_ctrl:1
	v_add_f32_dpp v137, v137, v137 row_ror:8 row_mask:0xf bank_mask:0xc
	v_add_f32_dpp v137, v129, v129 row_ror:8 row_mask:0xf bank_mask:0x3
	v_add_f32_dpp v12, v12, v12 row_ror:8 row_mask:0xf bank_mask:0xf bound_ctrl:1
	v_pk_fma_f32 v[6:7], v[92:93], v[12:13], v[48:49] op_sel_hi:[1,0,1] neg_lo:[1,0,0] neg_hi:[1,0,0]
	v_pk_fma_f32 v[8:9], v[94:95], v[12:13], v[50:51] op_sel_hi:[1,0,1] neg_lo:[1,0,0] neg_hi:[1,0,0]
	ds_read_b128 v[36:39], v10 offset:42240
	ds_read_b128 v[44:47], v10 offset:42752
	ds_read_b128 v[40:43], v10 offset:42496
	v_fma_mix_f32 v12, v6, v110, v180 op_sel_hi:[0,1,0]
	v_fma_mix_f32 v12, v7, v110, v12 op_sel:[0,1,0] op_sel_hi:[0,1,0]
	v_fma_mix_f32 v12, v8, v111, v12 op_sel_hi:[0,1,0]
	v_fma_mix_f32 v12, v9, v111, v12 op_sel:[0,1,0] op_sel_hi:[0,1,0]
	v_fma_mix_f32 v81, v6, v90, v180 op_sel_hi:[0,1,0]
	v_fma_mix_f32 v81, v7, v90, v81 op_sel:[0,1,0] op_sel_hi:[0,1,0]
	v_add_f32_dpp v12, v12, v12 row_ror:1 row_mask:0xf bank_mask:0xf bound_ctrl:1
	v_fma_mix_f32 v81, v8, v91, v81 op_sel_hi:[0,1,0]
	v_fma_mix_f32 v81, v9, v91, v81 op_sel:[0,1,0] op_sel_hi:[0,1,0]
	v_add_f32_dpp v12, v12, v12 row_ror:2 row_mask:0xf bank_mask:0xf bound_ctrl:1
	v_pk_fma_f32 v[48:49], v[118:119], v[72:73], v[6:7] op_sel:[0,1,0]
	v_pk_fma_f32 v[50:51], v[120:121], v[72:73], v[8:9] op_sel:[0,1,0]
	v_add_f32_dpp v12, v12, v12 row_ror:4 row_mask:0xf bank_mask:0xf bound_ctrl:1
	v_add_f32_dpp v134, v134, v134 row_ror:4 row_mask:0xf bank_mask:0xa
	v_add_f32_dpp v134, v130, v130 row_ror:12 row_mask:0xf bank_mask:0x5
	v_add_f32_dpp v135, v135, v135 row_ror:4 row_mask:0xf bank_mask:0xa
	v_add_f32_dpp v12, v12, v12 row_ror:8 row_mask:0xf bank_mask:0xf bound_ctrl:1
	v_pk_fma_f32 v[6:7], v[114:115], v[12:13], v[48:49] op_sel_hi:[1,0,1] neg_lo:[1,0,0] neg_hi:[1,0,0]
	v_pk_fma_f32 v[8:9], v[116:117], v[12:13], v[50:51] op_sel_hi:[1,0,1] neg_lo:[1,0,0] neg_hi:[1,0,0]
	v_pk_mul_f32 v[6:7], v[6:7], v[106:107]
	v_pk_mul_f32 v[8:9], v[8:9], v[108:109]
	s_waitcnt lgkmcnt(0)
	ds_read_b128 v[88:91], v10 offset:43264
	ds_read_b128 v[96:99], v10 offset:43776
	ds_read_b128 v[92:95], v10 offset:43520
	v_fma_mix_f32 v12, v6, v20, v180 op_sel_hi:[0,1,0]
	v_fma_mix_f32 v12, v7, v20, v12 op_sel:[0,1,0] op_sel_hi:[0,1,0]
	v_fma_mix_f32 v12, v8, v21, v12 op_sel_hi:[0,1,0]
	v_fma_mix_f32 v12, v9, v21, v12 op_sel:[0,1,0] op_sel_hi:[0,1,0]
	v_fma_mix_f32 v82, v6, v112, v180 op_sel_hi:[0,1,0]
	v_fma_mix_f32 v82, v7, v112, v82 op_sel:[0,1,0] op_sel_hi:[0,1,0]
	v_add_f32_dpp v12, v12, v12 row_ror:1 row_mask:0xf bank_mask:0xf bound_ctrl:1
	v_fma_mix_f32 v82, v8, v113, v82 op_sel_hi:[0,1,0]
	v_fma_mix_f32 v82, v9, v113, v82 op_sel:[0,1,0] op_sel_hi:[0,1,0]
	v_add_f32_dpp v12, v12, v12 row_ror:2 row_mask:0xf bank_mask:0xf bound_ctrl:1
	v_pk_fma_f32 v[48:49], v[28:29], v[66:67], v[6:7] op_sel_hi:[1,0,1]
	v_pk_fma_f32 v[50:51], v[30:31], v[66:67], v[8:9] op_sel_hi:[1,0,1]
	v_add_f32_dpp v12, v12, v12 row_ror:4 row_mask:0xf bank_mask:0xf bound_ctrl:1
	v_add_f32_dpp v135, v131, v131 row_ror:12 row_mask:0xf bank_mask:0x5
	v_add_f32_dpp v136, v136, v136 row_ror:4 row_mask:0xf bank_mask:0xa
	v_add_f32_dpp v136, v132, v132 row_ror:12 row_mask:0xf bank_mask:0x5
	v_add_f32_dpp v12, v12, v12 row_ror:8 row_mask:0xf bank_mask:0xf bound_ctrl:1
	v_pk_fma_f32 v[6:7], v[24:25], v[12:13], v[48:49] op_sel_hi:[1,0,1] neg_lo:[1,0,0] neg_hi:[1,0,0]
	v_pk_fma_f32 v[8:9], v[26:27], v[12:13], v[50:51] op_sel_hi:[1,0,1] neg_lo:[1,0,0] neg_hi:[1,0,0]
	ds_read_b128 v[110:113], v10 offset:44288
	ds_read_b128 v[106:109], v10 offset:44032
	ds_read_b128 v[118:121], v10 offset:44800
	ds_read_b128 v[114:117], v10 offset:44544
	ds_read_b128 v[70:73], v11 offset:2816
	v_fma_mix_f32 v12, v6, v36, v180 op_sel_hi:[0,1,0]
	v_fma_mix_f32 v12, v7, v36, v12 op_sel:[0,1,0] op_sel_hi:[0,1,0]
	v_fma_mix_f32 v12, v8, v37, v12 op_sel_hi:[0,1,0]
	v_fma_mix_f32 v12, v9, v37, v12 op_sel:[0,1,0] op_sel_hi:[0,1,0]
	v_fma_mix_f32 v83, v6, v22, v180 op_sel_hi:[0,1,0]
	v_fma_mix_f32 v83, v7, v22, v83 op_sel:[0,1,0] op_sel_hi:[0,1,0]
	v_add_f32_dpp v12, v12, v12 row_ror:1 row_mask:0xf bank_mask:0xf bound_ctrl:1
	v_fma_mix_f32 v83, v8, v23, v83 op_sel_hi:[0,1,0]
	v_fma_mix_f32 v83, v9, v23, v83 op_sel:[0,1,0] op_sel_hi:[0,1,0]
	v_add_f32_dpp v12, v12, v12 row_ror:2 row_mask:0xf bank_mask:0xf bound_ctrl:1
	v_pk_fma_f32 v[48:49], v[44:45], v[66:67], v[6:7] op_sel:[0,1,0]
	v_pk_fma_f32 v[50:51], v[46:47], v[66:67], v[8:9] op_sel:[0,1,0]
	v_add_f32_dpp v12, v12, v12 row_ror:4 row_mask:0xf bank_mask:0xf bound_ctrl:1
	v_add_f32_dpp v137, v137, v137 row_ror:4 row_mask:0xf bank_mask:0xa
	v_add_f32_dpp v137, v133, v133 row_ror:12 row_mask:0xf bank_mask:0x5
	v_add_f32_dpp v12, v12, v12 row_ror:8 row_mask:0xf bank_mask:0xf bound_ctrl:1
	v_pk_fma_f32 v[6:7], v[40:41], v[12:13], v[48:49] op_sel_hi:[1,0,1] neg_lo:[1,0,0] neg_hi:[1,0,0]
	v_pk_fma_f32 v[8:9], v[42:43], v[12:13], v[50:51] op_sel_hi:[1,0,1] neg_lo:[1,0,0] neg_hi:[1,0,0]
	s_waitcnt lgkmcnt(1)
	ds_read_b128 v[20:23], v10 offset:45312
	ds_read_b128 v[28:31], v10 offset:45824
	ds_read_b128 v[24:27], v10 offset:45568
	v_fma_mix_f32 v12, v6, v88, v180 op_sel_hi:[0,1,0]
	v_fma_mix_f32 v12, v7, v88, v12 op_sel:[0,1,0] op_sel_hi:[0,1,0]
	v_fma_mix_f32 v12, v8, v89, v12 op_sel_hi:[0,1,0]
	v_fma_mix_f32 v12, v9, v89, v12 op_sel:[0,1,0] op_sel_hi:[0,1,0]
	v_fma_mix_f32 v100, v6, v38, v180 op_sel_hi:[0,1,0]
	v_fma_mix_f32 v100, v7, v38, v100 op_sel:[0,1,0] op_sel_hi:[0,1,0]
	v_add_f32_dpp v12, v12, v12 row_ror:1 row_mask:0xf bank_mask:0xf bound_ctrl:1
	v_fma_mix_f32 v100, v8, v39, v100 op_sel_hi:[0,1,0]
	v_fma_mix_f32 v100, v9, v39, v100 op_sel:[0,1,0] op_sel_hi:[0,1,0]
	v_add_f32_dpp v12, v12, v12 row_ror:2 row_mask:0xf bank_mask:0xf bound_ctrl:1
	v_pk_fma_f32 v[48:49], v[96:97], v[68:69], v[6:7] op_sel_hi:[1,0,1]
	v_pk_fma_f32 v[50:51], v[98:99], v[68:69], v[8:9] op_sel_hi:[1,0,1]
	v_add_f32_dpp v12, v12, v12 row_ror:4 row_mask:0xf bank_mask:0xf bound_ctrl:1
	v_cndmask_b32_e64 v62, v136, v134, s[38:39]
	v_cndmask_b32_e64 v63, v134, v136, s[38:39]
	v_add_f32_dpp v12, v12, v12 row_ror:8 row_mask:0xf bank_mask:0xf bound_ctrl:1
	v_pk_fma_f32 v[6:7], v[92:93], v[12:13], v[48:49] op_sel_hi:[1,0,1] neg_lo:[1,0,0] neg_hi:[1,0,0]
	v_pk_fma_f32 v[8:9], v[94:95], v[12:13], v[50:51] op_sel_hi:[1,0,1] neg_lo:[1,0,0] neg_hi:[1,0,0]
	ds_read_b128 v[36:39], v10 offset:46336
	ds_read_b128 v[44:47], v10 offset:46848
	ds_read_b128 v[40:43], v10 offset:46592
	v_fma_mix_f32 v12, v6, v110, v180 op_sel_hi:[0,1,0]
	v_fma_mix_f32 v12, v7, v110, v12 op_sel:[0,1,0] op_sel_hi:[0,1,0]
	v_fma_mix_f32 v12, v8, v111, v12 op_sel_hi:[0,1,0]
	v_fma_mix_f32 v12, v9, v111, v12 op_sel:[0,1,0] op_sel_hi:[0,1,0]
	v_fma_mix_f32 v101, v6, v90, v180 op_sel_hi:[0,1,0]
	v_fma_mix_f32 v101, v7, v90, v101 op_sel:[0,1,0] op_sel_hi:[0,1,0]
	v_add_f32_dpp v12, v12, v12 row_ror:1 row_mask:0xf bank_mask:0xf bound_ctrl:1
	v_fma_mix_f32 v101, v8, v91, v101 op_sel_hi:[0,1,0]
	v_fma_mix_f32 v101, v9, v91, v101 op_sel:[0,1,0] op_sel_hi:[0,1,0]
	v_add_f32_dpp v12, v12, v12 row_ror:2 row_mask:0xf bank_mask:0xf bound_ctrl:1
	v_pk_fma_f32 v[48:49], v[118:119], v[68:69], v[6:7] op_sel:[0,1,0]
	v_pk_fma_f32 v[50:51], v[120:121], v[68:69], v[8:9] op_sel:[0,1,0]
	v_add_f32_dpp v12, v12, v12 row_ror:4 row_mask:0xf bank_mask:0xf bound_ctrl:1
	v_cndmask_b32_e64 v64, v137, v135, s[38:39]
	v_cndmask_b32_e64 v65, v135, v137, s[38:39]
	v_add_f32_dpp v12, v12, v12 row_ror:8 row_mask:0xf bank_mask:0xf bound_ctrl:1
	v_pk_fma_f32 v[6:7], v[114:115], v[12:13], v[48:49] op_sel_hi:[1,0,1] neg_lo:[1,0,0] neg_hi:[1,0,0]
	v_pk_fma_f32 v[8:9], v[116:117], v[12:13], v[50:51] op_sel_hi:[1,0,1] neg_lo:[1,0,0] neg_hi:[1,0,0]
	v_pk_mul_f32 v[6:7], v[6:7], v[106:107]
	v_pk_mul_f32 v[8:9], v[8:9], v[108:109]
	s_waitcnt lgkmcnt(0)
	ds_read_b128 v[88:91], v10 offset:47360
	ds_read_b128 v[96:99], v10 offset:47872
	ds_read_b128 v[92:95], v10 offset:47616
	v_fma_mix_f32 v12, v6, v20, v180 op_sel_hi:[0,1,0]
	v_fma_mix_f32 v12, v7, v20, v12 op_sel:[0,1,0] op_sel_hi:[0,1,0]
	v_fma_mix_f32 v12, v8, v21, v12 op_sel_hi:[0,1,0]
	v_fma_mix_f32 v12, v9, v21, v12 op_sel:[0,1,0] op_sel_hi:[0,1,0]
	v_fma_mix_f32 v102, v6, v112, v180 op_sel_hi:[0,1,0]
	v_fma_mix_f32 v102, v7, v112, v102 op_sel:[0,1,0] op_sel_hi:[0,1,0]
	v_add_f32_dpp v12, v12, v12 row_ror:1 row_mask:0xf bank_mask:0xf bound_ctrl:1
	v_fma_mix_f32 v102, v8, v113, v102 op_sel_hi:[0,1,0]
	v_fma_mix_f32 v102, v9, v113, v102 op_sel:[0,1,0] op_sel_hi:[0,1,0]
	v_add_f32_dpp v12, v12, v12 row_ror:2 row_mask:0xf bank_mask:0xf bound_ctrl:1
	v_pk_fma_f32 v[48:49], v[28:29], v[70:71], v[6:7] op_sel_hi:[1,0,1]
	v_pk_fma_f32 v[50:51], v[30:31], v[70:71], v[8:9] op_sel_hi:[1,0,1]
	v_add_f32_dpp v12, v12, v12 row_ror:4 row_mask:0xf bank_mask:0xf bound_ctrl:1
	v_add_f32_dpp v62, v63, v62 quad_perm:[2,3,0,1] row_mask:0xf bank_mask:0xf bound_ctrl:1
	v_add_f32_dpp v63, v65, v64 quad_perm:[2,3,0,1] row_mask:0xf bank_mask:0xf bound_ctrl:1
	v_add_f32_dpp v12, v12, v12 row_ror:8 row_mask:0xf bank_mask:0xf bound_ctrl:1
	v_pk_fma_f32 v[6:7], v[24:25], v[12:13], v[48:49] op_sel_hi:[1,0,1] neg_lo:[1,0,0] neg_hi:[1,0,0]
	v_pk_fma_f32 v[8:9], v[26:27], v[12:13], v[50:51] op_sel_hi:[1,0,1] neg_lo:[1,0,0] neg_hi:[1,0,0]
	ds_read_b128 v[110:113], v10 offset:48384
	ds_read_b128 v[106:109], v10 offset:48128
	ds_read_b128 v[118:121], v10 offset:48896
	ds_read_b128 v[114:117], v10 offset:48640
	ds_read_b128 v[66:69], v11 offset:3072
	v_fma_mix_f32 v12, v6, v36, v180 op_sel_hi:[0,1,0]
	v_fma_mix_f32 v12, v7, v36, v12 op_sel:[0,1,0] op_sel_hi:[0,1,0]
	v_fma_mix_f32 v12, v8, v37, v12 op_sel_hi:[0,1,0]
	v_fma_mix_f32 v12, v9, v37, v12 op_sel:[0,1,0] op_sel_hi:[0,1,0]
	v_fma_mix_f32 v103, v6, v22, v180 op_sel_hi:[0,1,0]
	v_fma_mix_f32 v103, v7, v22, v103 op_sel:[0,1,0] op_sel_hi:[0,1,0]
	v_add_f32_dpp v12, v12, v12 row_ror:1 row_mask:0xf bank_mask:0xf bound_ctrl:1
	v_fma_mix_f32 v103, v8, v23, v103 op_sel_hi:[0,1,0]
	v_fma_mix_f32 v103, v9, v23, v103 op_sel:[0,1,0] op_sel_hi:[0,1,0]
	v_add_f32_dpp v12, v12, v12 row_ror:2 row_mask:0xf bank_mask:0xf bound_ctrl:1
	v_pk_fma_f32 v[48:49], v[44:45], v[70:71], v[6:7] op_sel:[0,1,0]
	v_pk_fma_f32 v[50:51], v[46:47], v[70:71], v[8:9] op_sel:[0,1,0]
	v_add_f32_dpp v12, v12, v12 row_ror:4 row_mask:0xf bank_mask:0xf bound_ctrl:1
	v_cndmask_b32_e64 v65, v63, v62, s[40:41]
	v_cndmask_b32_e64 v62, v62, v63, s[40:41]
	v_add_f32_dpp v12, v12, v12 row_ror:8 row_mask:0xf bank_mask:0xf bound_ctrl:1
	v_pk_fma_f32 v[6:7], v[40:41], v[12:13], v[48:49] op_sel_hi:[1,0,1] neg_lo:[1,0,0] neg_hi:[1,0,0]
	v_pk_fma_f32 v[8:9], v[42:43], v[12:13], v[50:51] op_sel_hi:[1,0,1] neg_lo:[1,0,0] neg_hi:[1,0,0]
	s_waitcnt lgkmcnt(1)
	ds_read_b128 v[20:23], v10 offset:49408
	ds_read_b128 v[28:31], v10 offset:49920
	ds_read_b128 v[24:27], v10 offset:49664
	v_fma_mix_f32 v12, v6, v88, v180 op_sel_hi:[0,1,0]
	v_fma_mix_f32 v12, v7, v88, v12 op_sel:[0,1,0] op_sel_hi:[0,1,0]
	v_fma_mix_f32 v12, v8, v89, v12 op_sel_hi:[0,1,0]
	v_fma_mix_f32 v12, v9, v89, v12 op_sel:[0,1,0] op_sel_hi:[0,1,0]
	v_fma_mix_f32 v104, v6, v38, v180 op_sel_hi:[0,1,0]
	v_fma_mix_f32 v104, v7, v38, v104 op_sel:[0,1,0] op_sel_hi:[0,1,0]
	v_add_f32_dpp v12, v12, v12 row_ror:1 row_mask:0xf bank_mask:0xf bound_ctrl:1
	v_fma_mix_f32 v104, v8, v39, v104 op_sel_hi:[0,1,0]
	v_fma_mix_f32 v104, v9, v39, v104 op_sel:[0,1,0] op_sel_hi:[0,1,0]
	v_add_f32_dpp v12, v12, v12 row_ror:2 row_mask:0xf bank_mask:0xf bound_ctrl:1
	v_pk_fma_f32 v[48:49], v[96:97], v[72:73], v[6:7] op_sel_hi:[1,0,1]
	v_pk_fma_f32 v[50:51], v[98:99], v[72:73], v[8:9] op_sel_hi:[1,0,1]
	v_add_f32_dpp v12, v12, v12 row_ror:4 row_mask:0xf bank_mask:0xf bound_ctrl:1
	v_add_f32_dpp v62, v62, v65 quad_perm:[1,0,3,2] row_mask:0xf bank_mask:0xf bound_ctrl:1
	v_cvt_pk_bf16_f32 v62, v62, v62
	v_add_f32_dpp v12, v12, v12 row_ror:8 row_mask:0xf bank_mask:0xf bound_ctrl:1
	v_pk_fma_f32 v[6:7], v[92:93], v[12:13], v[48:49] op_sel_hi:[1,0,1] neg_lo:[1,0,0] neg_hi:[1,0,0]
	v_pk_fma_f32 v[8:9], v[94:95], v[12:13], v[50:51] op_sel_hi:[1,0,1] neg_lo:[1,0,0] neg_hi:[1,0,0]
	ds_read_b128 v[36:39], v10 offset:50432
	ds_read_b128 v[44:47], v10 offset:50944
	ds_read_b128 v[40:43], v10 offset:50688
	v_fma_mix_f32 v12, v6, v110, v180 op_sel_hi:[0,1,0]
	v_fma_mix_f32 v12, v7, v110, v12 op_sel:[0,1,0] op_sel_hi:[0,1,0]
	v_fma_mix_f32 v12, v8, v111, v12 op_sel_hi:[0,1,0]
	v_fma_mix_f32 v12, v9, v111, v12 op_sel:[0,1,0] op_sel_hi:[0,1,0]
	v_fma_mix_f32 v105, v6, v90, v180 op_sel_hi:[0,1,0]
	v_fma_mix_f32 v105, v7, v90, v105 op_sel:[0,1,0] op_sel_hi:[0,1,0]
	v_add_f32_dpp v12, v12, v12 row_ror:1 row_mask:0xf bank_mask:0xf bound_ctrl:1
	v_fma_mix_f32 v105, v8, v91, v105 op_sel_hi:[0,1,0]
	v_fma_mix_f32 v105, v9, v91, v105 op_sel:[0,1,0] op_sel_hi:[0,1,0]
	v_add_f32_dpp v12, v12, v12 row_ror:2 row_mask:0xf bank_mask:0xf bound_ctrl:1
	v_pk_fma_f32 v[48:49], v[118:119], v[72:73], v[6:7] op_sel:[0,1,0]
	v_pk_fma_f32 v[50:51], v[120:121], v[72:73], v[8:9] op_sel:[0,1,0]
	v_add_f32_dpp v12, v12, v12 row_ror:4 row_mask:0xf bank_mask:0xf bound_ctrl:1
	global_store_short v[2:3], v62, off
	v_lshl_add_u64 v[2:3], v[2:3], 0, s[84:85]
	v_add_f32_dpp v12, v12, v12 row_ror:8 row_mask:0xf bank_mask:0xf bound_ctrl:1
	v_pk_fma_f32 v[6:7], v[114:115], v[12:13], v[48:49] op_sel_hi:[1,0,1] neg_lo:[1,0,0] neg_hi:[1,0,0]
	v_pk_fma_f32 v[8:9], v[116:117], v[12:13], v[50:51] op_sel_hi:[1,0,1] neg_lo:[1,0,0] neg_hi:[1,0,0]
	v_pk_mul_f32 v[6:7], v[6:7], v[106:107]
	v_pk_mul_f32 v[8:9], v[8:9], v[108:109]
	s_waitcnt lgkmcnt(0)
	ds_read_b128 v[88:91], v10 offset:51456
	ds_read_b128 v[96:99], v10 offset:51968
	ds_read_b128 v[92:95], v10 offset:51712
	v_fma_mix_f32 v12, v6, v20, v180 op_sel_hi:[0,1,0]
	v_fma_mix_f32 v12, v7, v20, v12 op_sel:[0,1,0] op_sel_hi:[0,1,0]
	v_fma_mix_f32 v12, v8, v21, v12 op_sel_hi:[0,1,0]
	v_fma_mix_f32 v12, v9, v21, v12 op_sel:[0,1,0] op_sel_hi:[0,1,0]
	v_fma_mix_f32 v61, v6, v112, v180 op_sel_hi:[0,1,0]
	v_fma_mix_f32 v61, v7, v112, v61 op_sel:[0,1,0] op_sel_hi:[0,1,0]
	v_add_f32_dpp v12, v12, v12 row_ror:1 row_mask:0xf bank_mask:0xf bound_ctrl:1
	v_fma_mix_f32 v61, v8, v113, v61 op_sel_hi:[0,1,0]
	v_fma_mix_f32 v61, v9, v113, v61 op_sel:[0,1,0] op_sel_hi:[0,1,0]
	v_add_f32_dpp v12, v12, v12 row_ror:2 row_mask:0xf bank_mask:0xf bound_ctrl:1
	v_pk_fma_f32 v[48:49], v[28:29], v[66:67], v[6:7] op_sel_hi:[1,0,1]
	v_pk_fma_f32 v[50:51], v[30:31], v[66:67], v[8:9] op_sel_hi:[1,0,1]
	v_add_f32_dpp v12, v12, v12 row_ror:4 row_mask:0xf bank_mask:0xf bound_ctrl:1
	s_nop 1
	v_add_f32_dpp v12, v12, v12 row_ror:8 row_mask:0xf bank_mask:0xf bound_ctrl:1
	v_pk_fma_f32 v[6:7], v[24:25], v[12:13], v[48:49] op_sel_hi:[1,0,1] neg_lo:[1,0,0] neg_hi:[1,0,0]
	v_pk_fma_f32 v[8:9], v[26:27], v[12:13], v[50:51] op_sel_hi:[1,0,1] neg_lo:[1,0,0] neg_hi:[1,0,0]
	ds_read_b128 v[110:113], v10 offset:52480
	ds_read_b128 v[106:109], v10 offset:52224
	ds_read_b128 v[118:121], v10 offset:52992
	ds_read_b128 v[114:117], v10 offset:52736
	ds_read_b128 v[70:73], v11 offset:3328
	v_fma_mix_f32 v12, v6, v36, v180 op_sel_hi:[0,1,0]
	v_fma_mix_f32 v12, v7, v36, v12 op_sel:[0,1,0] op_sel_hi:[0,1,0]
	v_fma_mix_f32 v12, v8, v37, v12 op_sel_hi:[0,1,0]
	v_fma_mix_f32 v12, v9, v37, v12 op_sel:[0,1,0] op_sel_hi:[0,1,0]
	v_fma_mix_f32 v122, v6, v22, v180 op_sel_hi:[0,1,0]
	v_fma_mix_f32 v122, v7, v22, v122 op_sel:[0,1,0] op_sel_hi:[0,1,0]
	v_add_f32_dpp v12, v12, v12 row_ror:1 row_mask:0xf bank_mask:0xf bound_ctrl:1
	v_fma_mix_f32 v122, v8, v23, v122 op_sel_hi:[0,1,0]
	v_fma_mix_f32 v122, v9, v23, v122 op_sel:[0,1,0] op_sel_hi:[0,1,0]
	v_add_f32_dpp v12, v12, v12 row_ror:2 row_mask:0xf bank_mask:0xf bound_ctrl:1
	v_pk_fma_f32 v[48:49], v[44:45], v[66:67], v[6:7] op_sel:[0,1,0]
	v_pk_fma_f32 v[50:51], v[46:47], v[66:67], v[8:9] op_sel:[0,1,0]
	v_add_f32_dpp v12, v12, v12 row_ror:4 row_mask:0xf bank_mask:0xf bound_ctrl:1
	v_add_f32_dpp v83, v83, v83 row_ror:8 row_mask:0xf bank_mask:0xc
	v_add_f32_dpp v83, v52, v52 row_ror:8 row_mask:0xf bank_mask:0x3
	v_add_f32_dpp v100, v100, v100 row_ror:8 row_mask:0xf bank_mask:0xc
	v_add_f32_dpp v12, v12, v12 row_ror:8 row_mask:0xf bank_mask:0xf bound_ctrl:1
	v_pk_fma_f32 v[6:7], v[40:41], v[12:13], v[48:49] op_sel_hi:[1,0,1] neg_lo:[1,0,0] neg_hi:[1,0,0]
	v_pk_fma_f32 v[8:9], v[42:43], v[12:13], v[50:51] op_sel_hi:[1,0,1] neg_lo:[1,0,0] neg_hi:[1,0,0]
	s_waitcnt lgkmcnt(1)
	ds_read_b128 v[20:23], v10 offset:53504
	ds_read_b128 v[28:31], v10 offset:54016
	ds_read_b128 v[24:27], v10 offset:53760
	v_fma_mix_f32 v12, v6, v88, v180 op_sel_hi:[0,1,0]
	v_fma_mix_f32 v12, v7, v88, v12 op_sel:[0,1,0] op_sel_hi:[0,1,0]
	v_fma_mix_f32 v12, v8, v89, v12 op_sel_hi:[0,1,0]
	v_fma_mix_f32 v12, v9, v89, v12 op_sel:[0,1,0] op_sel_hi:[0,1,0]
	v_fma_mix_f32 v123, v6, v38, v180 op_sel_hi:[0,1,0]
	v_fma_mix_f32 v123, v7, v38, v123 op_sel:[0,1,0] op_sel_hi:[0,1,0]
	v_add_f32_dpp v12, v12, v12 row_ror:1 row_mask:0xf bank_mask:0xf bound_ctrl:1
	v_fma_mix_f32 v123, v8, v39, v123 op_sel_hi:[0,1,0]
	v_fma_mix_f32 v123, v9, v39, v123 op_sel:[0,1,0] op_sel_hi:[0,1,0]
	v_add_f32_dpp v12, v12, v12 row_ror:2 row_mask:0xf bank_mask:0xf bound_ctrl:1
	v_pk_fma_f32 v[48:49], v[96:97], v[68:69], v[6:7] op_sel_hi:[1,0,1]
	v_pk_fma_f32 v[50:51], v[98:99], v[68:69], v[8:9] op_sel_hi:[1,0,1]
	v_add_f32_dpp v12, v12, v12 row_ror:4 row_mask:0xf bank_mask:0xf bound_ctrl:1
	v_add_f32_dpp v100, v53, v53 row_ror:8 row_mask:0xf bank_mask:0x3
	v_add_f32_dpp v101, v101, v101 row_ror:8 row_mask:0xf bank_mask:0xc
	v_add_f32_dpp v101, v54, v54 row_ror:8 row_mask:0xf bank_mask:0x3
	v_add_f32_dpp v12, v12, v12 row_ror:8 row_mask:0xf bank_mask:0xf bound_ctrl:1
	v_pk_fma_f32 v[6:7], v[92:93], v[12:13], v[48:49] op_sel_hi:[1,0,1] neg_lo:[1,0,0] neg_hi:[1,0,0]
	v_pk_fma_f32 v[8:9], v[94:95], v[12:13], v[50:51] op_sel_hi:[1,0,1] neg_lo:[1,0,0] neg_hi:[1,0,0]
	ds_read_b128 v[36:39], v10 offset:54528
	ds_read_b128 v[44:47], v10 offset:55040
	ds_read_b128 v[40:43], v10 offset:54784
	v_fma_mix_f32 v12, v6, v110, v180 op_sel_hi:[0,1,0]
	v_fma_mix_f32 v12, v7, v110, v12 op_sel:[0,1,0] op_sel_hi:[0,1,0]
	v_fma_mix_f32 v12, v8, v111, v12 op_sel_hi:[0,1,0]
	v_fma_mix_f32 v12, v9, v111, v12 op_sel:[0,1,0] op_sel_hi:[0,1,0]
	v_fma_mix_f32 v124, v6, v90, v180 op_sel_hi:[0,1,0]
	v_fma_mix_f32 v124, v7, v90, v124 op_sel:[0,1,0] op_sel_hi:[0,1,0]
	v_add_f32_dpp v12, v12, v12 row_ror:1 row_mask:0xf bank_mask:0xf bound_ctrl:1
	v_fma_mix_f32 v124, v8, v91, v124 op_sel_hi:[0,1,0]
	v_fma_mix_f32 v124, v9, v91, v124 op_sel:[0,1,0] op_sel_hi:[0,1,0]
	v_add_f32_dpp v12, v12, v12 row_ror:2 row_mask:0xf bank_mask:0xf bound_ctrl:1
	v_pk_fma_f32 v[48:49], v[118:119], v[68:69], v[6:7] op_sel:[0,1,0]
	v_pk_fma_f32 v[50:51], v[120:121], v[68:69], v[8:9] op_sel:[0,1,0]
	v_add_f32_dpp v12, v12, v12 row_ror:4 row_mask:0xf bank_mask:0xf bound_ctrl:1
	v_add_f32_dpp v102, v102, v102 row_ror:8 row_mask:0xf bank_mask:0xc
	v_add_f32_dpp v102, v55, v55 row_ror:8 row_mask:0xf bank_mask:0x3
	v_add_f32_dpp v103, v103, v103 row_ror:8 row_mask:0xf bank_mask:0xc
	v_add_f32_dpp v12, v12, v12 row_ror:8 row_mask:0xf bank_mask:0xf bound_ctrl:1
	v_pk_fma_f32 v[6:7], v[114:115], v[12:13], v[48:49] op_sel_hi:[1,0,1] neg_lo:[1,0,0] neg_hi:[1,0,0]
	v_pk_fma_f32 v[8:9], v[116:117], v[12:13], v[50:51] op_sel_hi:[1,0,1] neg_lo:[1,0,0] neg_hi:[1,0,0]
	v_pk_mul_f32 v[6:7], v[6:7], v[106:107]
	v_pk_mul_f32 v[8:9], v[8:9], v[108:109]
	s_waitcnt lgkmcnt(0)
	ds_read_b128 v[88:91], v10 offset:55552
	ds_read_b128 v[96:99], v10 offset:56064
	ds_read_b128 v[92:95], v10 offset:55808
	v_fma_mix_f32 v12, v6, v20, v180 op_sel_hi:[0,1,0]
	v_fma_mix_f32 v12, v7, v20, v12 op_sel:[0,1,0] op_sel_hi:[0,1,0]
	v_fma_mix_f32 v12, v8, v21, v12 op_sel_hi:[0,1,0]
	v_fma_mix_f32 v12, v9, v21, v12 op_sel:[0,1,0] op_sel_hi:[0,1,0]
	v_fma_mix_f32 v125, v6, v112, v180 op_sel_hi:[0,1,0]
	v_fma_mix_f32 v125, v7, v112, v125 op_sel:[0,1,0] op_sel_hi:[0,1,0]
	v_add_f32_dpp v12, v12, v12 row_ror:1 row_mask:0xf bank_mask:0xf bound_ctrl:1
	v_fma_mix_f32 v125, v8, v113, v125 op_sel_hi:[0,1,0]
	v_fma_mix_f32 v125, v9, v113, v125 op_sel:[0,1,0] op_sel_hi:[0,1,0]
	v_add_f32_dpp v12, v12, v12 row_ror:2 row_mask:0xf bank_mask:0xf bound_ctrl:1
	v_pk_fma_f32 v[48:49], v[28:29], v[70:71], v[6:7] op_sel_hi:[1,0,1]
	v_pk_fma_f32 v[50:51], v[30:31], v[70:71], v[8:9] op_sel_hi:[1,0,1]
	v_add_f32_dpp v12, v12, v12 row_ror:4 row_mask:0xf bank_mask:0xf bound_ctrl:1
	v_add_f32_dpp v103, v56, v56 row_ror:8 row_mask:0xf bank_mask:0x3
	v_add_f32_dpp v104, v104, v104 row_ror:8 row_mask:0xf bank_mask:0xc
	v_add_f32_dpp v104, v57, v57 row_ror:8 row_mask:0xf bank_mask:0x3
	v_add_f32_dpp v12, v12, v12 row_ror:8 row_mask:0xf bank_mask:0xf bound_ctrl:1
	v_pk_fma_f32 v[6:7], v[24:25], v[12:13], v[48:49] op_sel_hi:[1,0,1] neg_lo:[1,0,0] neg_hi:[1,0,0]
	v_pk_fma_f32 v[8:9], v[26:27], v[12:13], v[50:51] op_sel_hi:[1,0,1] neg_lo:[1,0,0] neg_hi:[1,0,0]
	ds_read_b128 v[110:113], v10 offset:56576
	ds_read_b128 v[106:109], v10 offset:56320
	ds_read_b128 v[118:121], v10 offset:57088
	ds_read_b128 v[114:117], v10 offset:56832
	ds_read_b128 v[66:69], v11 offset:3584
	v_fma_mix_f32 v12, v6, v36, v180 op_sel_hi:[0,1,0]
	v_fma_mix_f32 v12, v7, v36, v12 op_sel:[0,1,0] op_sel_hi:[0,1,0]
	v_fma_mix_f32 v12, v8, v37, v12 op_sel_hi:[0,1,0]
	v_fma_mix_f32 v12, v9, v37, v12 op_sel:[0,1,0] op_sel_hi:[0,1,0]
	v_fma_mix_f32 v126, v6, v22, v180 op_sel_hi:[0,1,0]
	v_fma_mix_f32 v126, v7, v22, v126 op_sel:[0,1,0] op_sel_hi:[0,1,0]
	v_add_f32_dpp v12, v12, v12 row_ror:1 row_mask:0xf bank_mask:0xf bound_ctrl:1
	v_fma_mix_f32 v126, v8, v23, v126 op_sel_hi:[0,1,0]
	v_fma_mix_f32 v126, v9, v23, v126 op_sel:[0,1,0] op_sel_hi:[0,1,0]
	v_add_f32_dpp v12, v12, v12 row_ror:2 row_mask:0xf bank_mask:0xf bound_ctrl:1
	v_pk_fma_f32 v[48:49], v[44:45], v[70:71], v[6:7] op_sel:[0,1,0]
	v_pk_fma_f32 v[50:51], v[46:47], v[70:71], v[8:9] op_sel:[0,1,0]
	v_add_f32_dpp v12, v12, v12 row_ror:4 row_mask:0xf bank_mask:0xf bound_ctrl:1
	v_add_f32_dpp v105, v105, v105 row_ror:8 row_mask:0xf bank_mask:0xc
	v_add_f32_dpp v105, v81, v81 row_ror:8 row_mask:0xf bank_mask:0x3
	v_add_f32_dpp v12, v12, v12 row_ror:8 row_mask:0xf bank_mask:0xf bound_ctrl:1
	v_pk_fma_f32 v[6:7], v[40:41], v[12:13], v[48:49] op_sel_hi:[1,0,1] neg_lo:[1,0,0] neg_hi:[1,0,0]
	v_pk_fma_f32 v[8:9], v[42:43], v[12:13], v[50:51] op_sel_hi:[1,0,1] neg_lo:[1,0,0] neg_hi:[1,0,0]
	s_waitcnt lgkmcnt(1)
	ds_read_b128 v[20:23], v10 offset:57600
	ds_read_b128 v[28:31], v10 offset:58112
	ds_read_b128 v[24:27], v10 offset:57856
	v_fma_mix_f32 v12, v6, v88, v180 op_sel_hi:[0,1,0]
	v_fma_mix_f32 v12, v7, v88, v12 op_sel:[0,1,0] op_sel_hi:[0,1,0]
	v_fma_mix_f32 v12, v8, v89, v12 op_sel_hi:[0,1,0]
	v_fma_mix_f32 v12, v9, v89, v12 op_sel:[0,1,0] op_sel_hi:[0,1,0]
	v_fma_mix_f32 v127, v6, v38, v180 op_sel_hi:[0,1,0]
	v_fma_mix_f32 v127, v7, v38, v127 op_sel:[0,1,0] op_sel_hi:[0,1,0]
	v_add_f32_dpp v12, v12, v12 row_ror:1 row_mask:0xf bank_mask:0xf bound_ctrl:1
	v_fma_mix_f32 v127, v8, v39, v127 op_sel_hi:[0,1,0]
	v_fma_mix_f32 v127, v9, v39, v127 op_sel:[0,1,0] op_sel_hi:[0,1,0]
	v_add_f32_dpp v12, v12, v12 row_ror:2 row_mask:0xf bank_mask:0xf bound_ctrl:1
	v_pk_fma_f32 v[48:49], v[96:97], v[72:73], v[6:7] op_sel_hi:[1,0,1]
	v_pk_fma_f32 v[50:51], v[98:99], v[72:73], v[8:9] op_sel_hi:[1,0,1]
	v_add_f32_dpp v12, v12, v12 row_ror:4 row_mask:0xf bank_mask:0xf bound_ctrl:1
	v_add_f32_dpp v61, v61, v61 row_ror:8 row_mask:0xf bank_mask:0xc
	v_add_f32_dpp v61, v82, v82 row_ror:8 row_mask:0xf bank_mask:0x3
	v_add_f32_dpp v12, v12, v12 row_ror:8 row_mask:0xf bank_mask:0xf bound_ctrl:1
	v_pk_fma_f32 v[6:7], v[92:93], v[12:13], v[48:49] op_sel_hi:[1,0,1] neg_lo:[1,0,0] neg_hi:[1,0,0]
	v_pk_fma_f32 v[8:9], v[94:95], v[12:13], v[50:51] op_sel_hi:[1,0,1] neg_lo:[1,0,0] neg_hi:[1,0,0]
	ds_read_b128 v[36:39], v10 offset:58624
	ds_read_b128 v[44:47], v10 offset:59136
	ds_read_b128 v[40:43], v10 offset:58880
	v_fma_mix_f32 v12, v6, v110, v180 op_sel_hi:[0,1,0]
	v_fma_mix_f32 v12, v7, v110, v12 op_sel:[0,1,0] op_sel_hi:[0,1,0]
	v_fma_mix_f32 v12, v8, v111, v12 op_sel_hi:[0,1,0]
	v_fma_mix_f32 v12, v9, v111, v12 op_sel:[0,1,0] op_sel_hi:[0,1,0]
	v_fma_mix_f32 v128, v6, v90, v180 op_sel_hi:[0,1,0]
	v_fma_mix_f32 v128, v7, v90, v128 op_sel:[0,1,0] op_sel_hi:[0,1,0]
	v_add_f32_dpp v12, v12, v12 row_ror:1 row_mask:0xf bank_mask:0xf bound_ctrl:1
	v_fma_mix_f32 v128, v8, v91, v128 op_sel_hi:[0,1,0]
	v_fma_mix_f32 v128, v9, v91, v128 op_sel:[0,1,0] op_sel_hi:[0,1,0]
	v_add_f32_dpp v12, v12, v12 row_ror:2 row_mask:0xf bank_mask:0xf bound_ctrl:1
	v_pk_fma_f32 v[48:49], v[118:119], v[72:73], v[6:7] op_sel:[0,1,0]
	v_pk_fma_f32 v[50:51], v[120:121], v[72:73], v[8:9] op_sel:[0,1,0]
	v_add_f32_dpp v12, v12, v12 row_ror:4 row_mask:0xf bank_mask:0xf bound_ctrl:1
	v_add_f32_dpp v103, v103, v103 row_ror:4 row_mask:0xf bank_mask:0xa
	v_add_f32_dpp v103, v83, v83 row_ror:12 row_mask:0xf bank_mask:0x5
	v_add_f32_dpp v104, v104, v104 row_ror:4 row_mask:0xf bank_mask:0xa
	v_add_f32_dpp v12, v12, v12 row_ror:8 row_mask:0xf bank_mask:0xf bound_ctrl:1
	v_pk_fma_f32 v[6:7], v[114:115], v[12:13], v[48:49] op_sel_hi:[1,0,1] neg_lo:[1,0,0] neg_hi:[1,0,0]
	v_pk_fma_f32 v[8:9], v[116:117], v[12:13], v[50:51] op_sel_hi:[1,0,1] neg_lo:[1,0,0] neg_hi:[1,0,0]
	v_pk_mul_f32 v[6:7], v[6:7], v[106:107]
	v_pk_mul_f32 v[8:9], v[8:9], v[108:109]
	s_waitcnt lgkmcnt(0)
	ds_read_b128 v[88:91], v10 offset:59648
	ds_read_b128 v[96:99], v10 offset:60160
	ds_read_b128 v[92:95], v10 offset:59904
	v_fma_mix_f32 v12, v6, v20, v180 op_sel_hi:[0,1,0]
	v_fma_mix_f32 v12, v7, v20, v12 op_sel:[0,1,0] op_sel_hi:[0,1,0]
	v_fma_mix_f32 v12, v8, v21, v12 op_sel_hi:[0,1,0]
	v_fma_mix_f32 v12, v9, v21, v12 op_sel:[0,1,0] op_sel_hi:[0,1,0]
	v_fma_mix_f32 v129, v6, v112, v180 op_sel_hi:[0,1,0]
	v_fma_mix_f32 v129, v7, v112, v129 op_sel:[0,1,0] op_sel_hi:[0,1,0]
	v_add_f32_dpp v12, v12, v12 row_ror:1 row_mask:0xf bank_mask:0xf bound_ctrl:1
	v_fma_mix_f32 v129, v8, v113, v129 op_sel_hi:[0,1,0]
	v_fma_mix_f32 v129, v9, v113, v129 op_sel:[0,1,0] op_sel_hi:[0,1,0]
	v_add_f32_dpp v12, v12, v12 row_ror:2 row_mask:0xf bank_mask:0xf bound_ctrl:1
	v_pk_fma_f32 v[48:49], v[28:29], v[66:67], v[6:7] op_sel_hi:[1,0,1]
	v_pk_fma_f32 v[50:51], v[30:31], v[66:67], v[8:9] op_sel_hi:[1,0,1]
	v_add_f32_dpp v12, v12, v12 row_ror:4 row_mask:0xf bank_mask:0xf bound_ctrl:1
	v_add_f32_dpp v104, v100, v100 row_ror:12 row_mask:0xf bank_mask:0x5
	v_add_f32_dpp v105, v105, v105 row_ror:4 row_mask:0xf bank_mask:0xa
	v_add_f32_dpp v105, v101, v101 row_ror:12 row_mask:0xf bank_mask:0x5
	v_add_f32_dpp v12, v12, v12 row_ror:8 row_mask:0xf bank_mask:0xf bound_ctrl:1
	v_pk_fma_f32 v[6:7], v[24:25], v[12:13], v[48:49] op_sel_hi:[1,0,1] neg_lo:[1,0,0] neg_hi:[1,0,0]
	v_pk_fma_f32 v[8:9], v[26:27], v[12:13], v[50:51] op_sel_hi:[1,0,1] neg_lo:[1,0,0] neg_hi:[1,0,0]
	ds_read_b128 v[110:113], v10 offset:60672
	ds_read_b128 v[106:109], v10 offset:60416
	ds_read_b128 v[118:121], v10 offset:61184
	ds_read_b128 v[114:117], v10 offset:60928
	ds_read_b128 v[70:73], v11 offset:3840
	v_fma_mix_f32 v12, v6, v36, v180 op_sel_hi:[0,1,0]
	v_fma_mix_f32 v12, v7, v36, v12 op_sel:[0,1,0] op_sel_hi:[0,1,0]
	v_fma_mix_f32 v12, v8, v37, v12 op_sel_hi:[0,1,0]
	v_fma_mix_f32 v12, v9, v37, v12 op_sel:[0,1,0] op_sel_hi:[0,1,0]
	v_fma_mix_f32 v130, v6, v22, v180 op_sel_hi:[0,1,0]
	v_fma_mix_f32 v130, v7, v22, v130 op_sel:[0,1,0] op_sel_hi:[0,1,0]
	v_add_f32_dpp v12, v12, v12 row_ror:1 row_mask:0xf bank_mask:0xf bound_ctrl:1
	v_fma_mix_f32 v130, v8, v23, v130 op_sel_hi:[0,1,0]
	v_fma_mix_f32 v130, v9, v23, v130 op_sel:[0,1,0] op_sel_hi:[0,1,0]
	v_add_f32_dpp v12, v12, v12 row_ror:2 row_mask:0xf bank_mask:0xf bound_ctrl:1
	v_pk_fma_f32 v[48:49], v[44:45], v[66:67], v[6:7] op_sel:[0,1,0]
	v_pk_fma_f32 v[50:51], v[46:47], v[66:67], v[8:9] op_sel:[0,1,0]
	v_add_f32_dpp v12, v12, v12 row_ror:4 row_mask:0xf bank_mask:0xf bound_ctrl:1
	v_add_f32_dpp v61, v61, v61 row_ror:4 row_mask:0xf bank_mask:0xa
	v_add_f32_dpp v61, v102, v102 row_ror:12 row_mask:0xf bank_mask:0x5
	v_add_f32_dpp v12, v12, v12 row_ror:8 row_mask:0xf bank_mask:0xf bound_ctrl:1
	v_pk_fma_f32 v[6:7], v[40:41], v[12:13], v[48:49] op_sel_hi:[1,0,1] neg_lo:[1,0,0] neg_hi:[1,0,0]
	v_pk_fma_f32 v[8:9], v[42:43], v[12:13], v[50:51] op_sel_hi:[1,0,1] neg_lo:[1,0,0] neg_hi:[1,0,0]
	s_waitcnt lgkmcnt(1)
	ds_read_b128 v[20:23], v10 offset:61696
	ds_read_b128 v[28:31], v10 offset:62208
	ds_read_b128 v[24:27], v10 offset:61952
	v_fma_mix_f32 v12, v6, v88, v180 op_sel_hi:[0,1,0]
	v_fma_mix_f32 v12, v7, v88, v12 op_sel:[0,1,0] op_sel_hi:[0,1,0]
	v_fma_mix_f32 v12, v8, v89, v12 op_sel_hi:[0,1,0]
	v_fma_mix_f32 v12, v9, v89, v12 op_sel:[0,1,0] op_sel_hi:[0,1,0]
	v_fma_mix_f32 v131, v6, v38, v180 op_sel_hi:[0,1,0]
	v_fma_mix_f32 v131, v7, v38, v131 op_sel:[0,1,0] op_sel_hi:[0,1,0]
	v_add_f32_dpp v12, v12, v12 row_ror:1 row_mask:0xf bank_mask:0xf bound_ctrl:1
	v_fma_mix_f32 v131, v8, v39, v131 op_sel_hi:[0,1,0]
	v_fma_mix_f32 v131, v9, v39, v131 op_sel:[0,1,0] op_sel_hi:[0,1,0]
	v_add_f32_dpp v12, v12, v12 row_ror:2 row_mask:0xf bank_mask:0xf bound_ctrl:1
	v_pk_fma_f32 v[48:49], v[96:97], v[68:69], v[6:7] op_sel_hi:[1,0,1]
	v_pk_fma_f32 v[50:51], v[98:99], v[68:69], v[8:9] op_sel_hi:[1,0,1]
	v_add_f32_dpp v12, v12, v12 row_ror:4 row_mask:0xf bank_mask:0xf bound_ctrl:1
	v_cndmask_b32_e64 v62, v105, v103, s[38:39]
	v_cndmask_b32_e64 v63, v103, v105, s[38:39]
	v_add_f32_dpp v12, v12, v12 row_ror:8 row_mask:0xf bank_mask:0xf bound_ctrl:1
	v_pk_fma_f32 v[6:7], v[92:93], v[12:13], v[48:49] op_sel_hi:[1,0,1] neg_lo:[1,0,0] neg_hi:[1,0,0]
	v_pk_fma_f32 v[8:9], v[94:95], v[12:13], v[50:51] op_sel_hi:[1,0,1] neg_lo:[1,0,0] neg_hi:[1,0,0]
	ds_read_b128 v[36:39], v10 offset:62720
	ds_read_b128 v[44:47], v10 offset:63232
	ds_read_b128 v[40:43], v10 offset:62976
	v_fma_mix_f32 v12, v6, v110, v180 op_sel_hi:[0,1,0]
	v_fma_mix_f32 v12, v7, v110, v12 op_sel:[0,1,0] op_sel_hi:[0,1,0]
	v_fma_mix_f32 v12, v8, v111, v12 op_sel_hi:[0,1,0]
	v_fma_mix_f32 v12, v9, v111, v12 op_sel:[0,1,0] op_sel_hi:[0,1,0]
	v_fma_mix_f32 v132, v6, v90, v180 op_sel_hi:[0,1,0]
	v_fma_mix_f32 v132, v7, v90, v132 op_sel:[0,1,0] op_sel_hi:[0,1,0]
	v_add_f32_dpp v12, v12, v12 row_ror:1 row_mask:0xf bank_mask:0xf bound_ctrl:1
	v_fma_mix_f32 v132, v8, v91, v132 op_sel_hi:[0,1,0]
	v_fma_mix_f32 v132, v9, v91, v132 op_sel:[0,1,0] op_sel_hi:[0,1,0]
	v_add_f32_dpp v12, v12, v12 row_ror:2 row_mask:0xf bank_mask:0xf bound_ctrl:1
	v_pk_fma_f32 v[48:49], v[118:119], v[68:69], v[6:7] op_sel:[0,1,0]
	v_pk_fma_f32 v[50:51], v[120:121], v[68:69], v[8:9] op_sel:[0,1,0]
	v_add_f32_dpp v12, v12, v12 row_ror:4 row_mask:0xf bank_mask:0xf bound_ctrl:1
	v_cndmask_b32_e64 v64, v61, v104, s[38:39]
	v_cndmask_b32_e64 v65, v104, v61, s[38:39]
	v_add_f32_dpp v12, v12, v12 row_ror:8 row_mask:0xf bank_mask:0xf bound_ctrl:1
	v_pk_fma_f32 v[6:7], v[114:115], v[12:13], v[48:49] op_sel_hi:[1,0,1] neg_lo:[1,0,0] neg_hi:[1,0,0]
	v_pk_fma_f32 v[8:9], v[116:117], v[12:13], v[50:51] op_sel_hi:[1,0,1] neg_lo:[1,0,0] neg_hi:[1,0,0]
	v_pk_mul_f32 v[6:7], v[6:7], v[106:107]
	v_pk_mul_f32 v[8:9], v[8:9], v[108:109]
	s_waitcnt lgkmcnt(0)
	ds_read_b128 v[88:91], v10 offset:63744
	ds_read_b128 v[96:99], v10 offset:64256
	ds_read_b128 v[92:95], v10 offset:64000
	v_fma_mix_f32 v12, v6, v20, v180 op_sel_hi:[0,1,0]
	v_fma_mix_f32 v12, v7, v20, v12 op_sel:[0,1,0] op_sel_hi:[0,1,0]
	v_fma_mix_f32 v12, v8, v21, v12 op_sel_hi:[0,1,0]
	v_fma_mix_f32 v12, v9, v21, v12 op_sel:[0,1,0] op_sel_hi:[0,1,0]
	v_fma_mix_f32 v133, v6, v112, v180 op_sel_hi:[0,1,0]
	v_fma_mix_f32 v133, v7, v112, v133 op_sel:[0,1,0] op_sel_hi:[0,1,0]
	v_add_f32_dpp v12, v12, v12 row_ror:1 row_mask:0xf bank_mask:0xf bound_ctrl:1
	v_fma_mix_f32 v133, v8, v113, v133 op_sel_hi:[0,1,0]
	v_fma_mix_f32 v133, v9, v113, v133 op_sel:[0,1,0] op_sel_hi:[0,1,0]
	v_add_f32_dpp v12, v12, v12 row_ror:2 row_mask:0xf bank_mask:0xf bound_ctrl:1
	v_pk_fma_f32 v[48:49], v[28:29], v[70:71], v[6:7] op_sel_hi:[1,0,1]
	v_pk_fma_f32 v[50:51], v[30:31], v[70:71], v[8:9] op_sel_hi:[1,0,1]
	v_add_f32_dpp v12, v12, v12 row_ror:4 row_mask:0xf bank_mask:0xf bound_ctrl:1
	v_add_f32_dpp v62, v63, v62 quad_perm:[2,3,0,1] row_mask:0xf bank_mask:0xf bound_ctrl:1
	v_add_f32_dpp v63, v65, v64 quad_perm:[2,3,0,1] row_mask:0xf bank_mask:0xf bound_ctrl:1
	v_add_f32_dpp v12, v12, v12 row_ror:8 row_mask:0xf bank_mask:0xf bound_ctrl:1
	v_pk_fma_f32 v[6:7], v[24:25], v[12:13], v[48:49] op_sel_hi:[1,0,1] neg_lo:[1,0,0] neg_hi:[1,0,0]
	v_pk_fma_f32 v[8:9], v[26:27], v[12:13], v[50:51] op_sel_hi:[1,0,1] neg_lo:[1,0,0] neg_hi:[1,0,0]
	ds_read_b128 v[110:113], v10 offset:64768
	ds_read_b128 v[106:109], v10 offset:64512
	ds_read_b128 v[118:121], v10 offset:65280
	ds_read_b128 v[114:117], v10 offset:65024
	v_fma_mix_f32 v12, v6, v36, v180 op_sel_hi:[0,1,0]
	v_fma_mix_f32 v12, v7, v36, v12 op_sel:[0,1,0] op_sel_hi:[0,1,0]
	v_fma_mix_f32 v12, v8, v37, v12 op_sel_hi:[0,1,0]
	v_fma_mix_f32 v12, v9, v37, v12 op_sel:[0,1,0] op_sel_hi:[0,1,0]
	v_fma_mix_f32 v134, v6, v22, v180 op_sel_hi:[0,1,0]
	v_fma_mix_f32 v134, v7, v22, v134 op_sel:[0,1,0] op_sel_hi:[0,1,0]
	v_add_f32_dpp v12, v12, v12 row_ror:1 row_mask:0xf bank_mask:0xf bound_ctrl:1
	v_fma_mix_f32 v134, v8, v23, v134 op_sel_hi:[0,1,0]
	v_fma_mix_f32 v134, v9, v23, v134 op_sel:[0,1,0] op_sel_hi:[0,1,0]
	v_add_f32_dpp v12, v12, v12 row_ror:2 row_mask:0xf bank_mask:0xf bound_ctrl:1
	v_pk_fma_f32 v[48:49], v[44:45], v[70:71], v[6:7] op_sel:[0,1,0]
	v_pk_fma_f32 v[50:51], v[46:47], v[70:71], v[8:9] op_sel:[0,1,0]
	v_add_f32_dpp v12, v12, v12 row_ror:4 row_mask:0xf bank_mask:0xf bound_ctrl:1
	v_cndmask_b32_e64 v65, v63, v62, s[40:41]
	v_cndmask_b32_e64 v62, v62, v63, s[40:41]
	v_add_f32_dpp v12, v12, v12 row_ror:8 row_mask:0xf bank_mask:0xf bound_ctrl:1
	v_pk_fma_f32 v[6:7], v[40:41], v[12:13], v[48:49] op_sel_hi:[1,0,1] neg_lo:[1,0,0] neg_hi:[1,0,0]
	v_pk_fma_f32 v[8:9], v[42:43], v[12:13], v[50:51] op_sel_hi:[1,0,1] neg_lo:[1,0,0] neg_hi:[1,0,0]
	s_waitcnt lgkmcnt(0)
	v_fma_mix_f32 v12, v6, v88, v180 op_sel_hi:[0,1,0]
	v_fma_mix_f32 v12, v7, v88, v12 op_sel:[0,1,0] op_sel_hi:[0,1,0]
	v_fma_mix_f32 v12, v8, v89, v12 op_sel_hi:[0,1,0]
	v_fma_mix_f32 v12, v9, v89, v12 op_sel:[0,1,0] op_sel_hi:[0,1,0]
	v_fma_mix_f32 v135, v6, v38, v180 op_sel_hi:[0,1,0]
	v_fma_mix_f32 v135, v7, v38, v135 op_sel:[0,1,0] op_sel_hi:[0,1,0]
	v_add_f32_dpp v12, v12, v12 row_ror:1 row_mask:0xf bank_mask:0xf bound_ctrl:1
	v_fma_mix_f32 v135, v8, v39, v135 op_sel_hi:[0,1,0]
	v_fma_mix_f32 v135, v9, v39, v135 op_sel:[0,1,0] op_sel_hi:[0,1,0]
	v_add_f32_dpp v12, v12, v12 row_ror:2 row_mask:0xf bank_mask:0xf bound_ctrl:1
	v_pk_fma_f32 v[48:49], v[96:97], v[72:73], v[6:7] op_sel_hi:[1,0,1]
	v_pk_fma_f32 v[50:51], v[98:99], v[72:73], v[8:9] op_sel_hi:[1,0,1]
	v_add_f32_dpp v12, v12, v12 row_ror:4 row_mask:0xf bank_mask:0xf bound_ctrl:1
	v_add_f32_dpp v62, v62, v65 quad_perm:[1,0,3,2] row_mask:0xf bank_mask:0xf bound_ctrl:1
	v_cvt_pk_bf16_f32 v62, v62, v62
	v_add_f32_dpp v12, v12, v12 row_ror:8 row_mask:0xf bank_mask:0xf bound_ctrl:1
	v_pk_fma_f32 v[6:7], v[92:93], v[12:13], v[48:49] op_sel_hi:[1,0,1] neg_lo:[1,0,0] neg_hi:[1,0,0]
	v_pk_fma_f32 v[8:9], v[94:95], v[12:13], v[50:51] op_sel_hi:[1,0,1] neg_lo:[1,0,0] neg_hi:[1,0,0]
	s_waitcnt lgkmcnt(0)
	s_barrier
	v_xor_b32_e32 v10, 0x10000, v10
	v_xor_b32_e32 v11, 0x1000, v11
	ds_read_b128 v[66:69], v11 offset:0
	ds_read_b128 v[20:23], v10 offset:256
	ds_read_b128 v[28:31], v10 offset:768
	ds_read_b128 v[24:27], v10 offset:512
	ds_read_b128 v[36:39], v10 offset:1280
	ds_read_b128 v[44:47], v10 offset:1792
	ds_read_b128 v[40:43], v10 offset:1536
	v_fma_mix_f32 v12, v6, v110, v180 op_sel_hi:[0,1,0]
	v_fma_mix_f32 v12, v7, v110, v12 op_sel:[0,1,0] op_sel_hi:[0,1,0]
	v_fma_mix_f32 v12, v8, v111, v12 op_sel_hi:[0,1,0]
	v_fma_mix_f32 v12, v9, v111, v12 op_sel:[0,1,0] op_sel_hi:[0,1,0]
	v_fma_mix_f32 v136, v6, v90, v180 op_sel_hi:[0,1,0]
	v_fma_mix_f32 v136, v7, v90, v136 op_sel:[0,1,0] op_sel_hi:[0,1,0]
	v_add_f32_dpp v12, v12, v12 row_ror:1 row_mask:0xf bank_mask:0xf bound_ctrl:1
	v_fma_mix_f32 v136, v8, v91, v136 op_sel_hi:[0,1,0]
	v_fma_mix_f32 v136, v9, v91, v136 op_sel:[0,1,0] op_sel_hi:[0,1,0]
	v_add_f32_dpp v12, v12, v12 row_ror:2 row_mask:0xf bank_mask:0xf bound_ctrl:1
	v_pk_fma_f32 v[48:49], v[118:119], v[72:73], v[6:7] op_sel:[0,1,0]
	v_pk_fma_f32 v[50:51], v[120:121], v[72:73], v[8:9] op_sel:[0,1,0]
	v_add_f32_dpp v12, v12, v12 row_ror:4 row_mask:0xf bank_mask:0xf bound_ctrl:1
	global_store_short v[2:3], v62, off
	v_lshl_add_u64 v[2:3], v[2:3], 0, s[84:85]
	v_add_f32_dpp v12, v12, v12 row_ror:8 row_mask:0xf bank_mask:0xf bound_ctrl:1
	v_pk_fma_f32 v[6:7], v[114:115], v[12:13], v[48:49] op_sel_hi:[1,0,1] neg_lo:[1,0,0] neg_hi:[1,0,0]
	v_pk_fma_f32 v[8:9], v[116:117], v[12:13], v[50:51] op_sel_hi:[1,0,1] neg_lo:[1,0,0] neg_hi:[1,0,0]
	v_pk_mul_f32 v[6:7], v[6:7], v[106:107]
	v_pk_mul_f32 v[8:9], v[8:9], v[108:109]
	v_fma_mix_f32 v137, v6, v112, v180 op_sel_hi:[0,1,0]
	v_fma_mix_f32 v137, v7, v112, v137 op_sel:[0,1,0] op_sel_hi:[0,1,0]
	v_fma_mix_f32 v137, v8, v113, v137 op_sel_hi:[0,1,0]
	v_fma_mix_f32 v137, v9, v113, v137 op_sel:[0,1,0] op_sel_hi:[0,1,0]
	v_mov_b32_e32 v170, v2
	v_mov_b32_e32 v171, v3
	s_mov_b64 s[100:101], -1
	s_cmp_lg_u32 s28, 0x800000
	s_cbranch_scc1 .Lscan_cons_chunk
	v_add_f32_dpp v130, v130, v130 row_ror:8 row_mask:0xf bank_mask:0xc
	v_add_f32_dpp v130, v122, v122 row_ror:8 row_mask:0xf bank_mask:0x3
	v_add_f32_dpp v131, v131, v131 row_ror:8 row_mask:0xf bank_mask:0xc
	v_add_f32_dpp v131, v123, v123 row_ror:8 row_mask:0xf bank_mask:0x3
	v_add_f32_dpp v132, v132, v132 row_ror:8 row_mask:0xf bank_mask:0xc
	v_add_f32_dpp v132, v124, v124 row_ror:8 row_mask:0xf bank_mask:0x3
	v_add_f32_dpp v133, v133, v133 row_ror:8 row_mask:0xf bank_mask:0xc
	v_add_f32_dpp v133, v125, v125 row_ror:8 row_mask:0xf bank_mask:0x3
	v_add_f32_dpp v134, v134, v134 row_ror:8 row_mask:0xf bank_mask:0xc
	v_add_f32_dpp v134, v126, v126 row_ror:8 row_mask:0xf bank_mask:0x3
	v_add_f32_dpp v135, v135, v135 row_ror:8 row_mask:0xf bank_mask:0xc
	v_add_f32_dpp v135, v127, v127 row_ror:8 row_mask:0xf bank_mask:0x3
	v_add_f32_dpp v136, v136, v136 row_ror:8 row_mask:0xf bank_mask:0xc
	v_add_f32_dpp v136, v128, v128 row_ror:8 row_mask:0xf bank_mask:0x3
	v_add_f32_dpp v137, v137, v137 row_ror:8 row_mask:0xf bank_mask:0xc
	v_add_f32_dpp v137, v129, v129 row_ror:8 row_mask:0xf bank_mask:0x3
	v_add_f32_dpp v134, v134, v134 row_ror:4 row_mask:0xf bank_mask:0xa
	v_add_f32_dpp v134, v130, v130 row_ror:12 row_mask:0xf bank_mask:0x5
	v_add_f32_dpp v135, v135, v135 row_ror:4 row_mask:0xf bank_mask:0xa
	v_add_f32_dpp v135, v131, v131 row_ror:12 row_mask:0xf bank_mask:0x5
	v_add_f32_dpp v136, v136, v136 row_ror:4 row_mask:0xf bank_mask:0xa
	v_add_f32_dpp v136, v132, v132 row_ror:12 row_mask:0xf bank_mask:0x5
	v_add_f32_dpp v137, v137, v137 row_ror:4 row_mask:0xf bank_mask:0xa
	v_add_f32_dpp v137, v133, v133 row_ror:12 row_mask:0xf bank_mask:0x5
	v_cndmask_b32_e64 v62, v136, v134, s[38:39]
	v_cndmask_b32_e64 v63, v134, v136, s[38:39]
	v_cndmask_b32_e64 v64, v137, v135, s[38:39]
	v_cndmask_b32_e64 v65, v135, v137, s[38:39]
	v_add_f32_dpp v62, v63, v62 quad_perm:[2,3,0,1] row_mask:0xf bank_mask:0xf bound_ctrl:1
	s_nop 0
	v_add_f32_dpp v63, v65, v64 quad_perm:[2,3,0,1] row_mask:0xf bank_mask:0xf bound_ctrl:1
	v_cndmask_b32_e64 v65, v63, v62, s[40:41]
	v_cndmask_b32_e64 v62, v62, v63, s[40:41]
	s_nop 1
	v_add_f32_dpp v62, v62, v65 quad_perm:[1,0,3,2] row_mask:0xf bank_mask:0xf bound_ctrl:1
	v_cvt_pk_bf16_f32 v62, v62, v62
	global_store_short v[2:3], v62, off
	s_branch .LBB0_53
